# GEMM tile loop: dropped the full vmcnt drain before each K-loop (counted waits of the loop already cover the staged tiles)
# baseline (speedup 1.0000x reference)
; #define PG8_STAGE(bufoff, gbase, voff) do { _Pragma("unroll") for (int _i = 0; _i < 2; ++_i) \
;         __builtin_amdgcn_global_load_lds((const unsigned*)((const char*)(gbase) + (voff)[_i]), (LAS unsigned*)(lds + (bufoff) + ldsw + _i * 8192), 16, 0, 0); } while (0)
; #define PG8_LDA(dst, b, h) do { _Pragma("unroll") for (int m = 0; m < 4; ++m) _Pragma("unroll") for (int k = 0; k < 2; ++k) dst[m][k] = *(const LAS bf16x8*)(lds + PG8_SA(b, h) + aoff + m * 2048 + k * 1024); } while (0)
; #define PG8_LDB(dst, b, h) do { _Pragma("unroll") for (int n = 0; n < 2; ++n) _Pragma("unroll") for (int k = 0; k < 2; ++k) dst[n][k] = *(const LAS bf16x8*)(lds + PG8_SB(b, h) + boff + n * 2048 + k * 1024); } while (0)
; #define PG8_MMA(ai, bj, At, Bt) do { __builtin_amdgcn_s_setprio(1); _Pragma("unroll") for (int m = 0; m < 4; ++m) _Pragma("unroll") for (int n = 0; n < 2; ++n) _Pragma("unroll") for (int k = 0; k < 2; ++k) \
;         acc[ai][bj][m][n] = __builtin_amdgcn_mfma_f32_16x16x32_bf16(Bt[n][k], At[m][k], acc[ai][bj][m][n], 0, 0, 0); __builtin_amdgcn_s_setprio(0); } while (0)
; #define PG8_WAIT_L(n) asm volatile("s_waitcnt lgkmcnt(" #n ")" ::: "memory")
; #define PG8_BAR __builtin_amdgcn_s_barrier()
; #define PG8_SCHED __builtin_amdgcn_sched_barrier(0)
; template <class F>
; DI void gemm_phase(const int tid, LAS unsigned char* lds, const bf16_t* Ap, int lda, const bf16_t* Bp, int ldb, int M, int N, int K, int G, int c, bool direct, const F& E) {
;     ...
;         for (int t = 0; t < nt; t += 2) {
;             const bool last = (t == nt - 2);
;             const char* a1 = cA + (size_t)(t + 1) * kstep;
;             const char* a2 = last ? nA : cA + (size_t)(t + 2) * kstep; const char* b2 = last ? nB : cB + (size_t)(t + 2) * kstep;
;             const char* a3 = a2 + kstep; const char* b3 = b2 + kstep;
;             PG8_LDB(B0, 0, 0); PG8_SCHED; PG8_LDA(At, 0, 0); PG8_STAGE(PG8_SA(1, 1), a1 + hsA, voffA);
;             PG8_WAIT_L(8); PG8_BAR; PG8_WAIT_L(0); PG8_MMA(0, 0, At, B0); PG8_BAR; PG8_SCHED;
;     ...
; #pragma unroll
;         for (int a = 0; a < 2; ++a)
; #pragma unroll
;             for (int b = 0; b < 2; ++b)
; #pragma unroll
;                 for (int m = 0; m < 4; ++m)
; #pragma unroll
;                     for (int n = 0; n < 2; ++n) acc[a][b][m][n] = (f32x4){0.f, 0.f, 0.f, 0.f};
;         cur = nxt; cA = nA; cB = nB; ++ui;
.LBB0_656:
	s_add_u32 s74, s74, 0x80
	s_addc_u32 s75, s75, 0
	s_add_u32 s71, s76, 0x100
	v_mov_b32_e32 v20, 0
	s_addc_u32 s80, s77, 0
	s_mov_b32 s76, 0
	v_mov_b32_e32 v21, v20
	v_mov_b32_e32 v22, v20
	v_mov_b32_e32 v23, v20
	v_mov_b32_e32 v24, v20
	v_mov_b32_e32 v25, v20
	v_mov_b32_e32 v26, v20
	v_mov_b32_e32 v27, v20
	v_mov_b32_e32 v44, v20
	v_mov_b32_e32 v45, v20
	v_mov_b32_e32 v46, v20
	v_mov_b32_e32 v47, v20
	v_mov_b32_e32 v48, v20
	v_mov_b32_e32 v49, v20
	v_mov_b32_e32 v50, v20
	v_mov_b32_e32 v51, v20
	v_mov_b32_e32 v0, v20
	v_mov_b32_e32 v1, v20
	v_mov_b32_e32 v2, v20
	v_mov_b32_e32 v3, v20
	v_mov_b32_e32 v12, v20
	v_mov_b32_e32 v13, v20
	v_mov_b32_e32 v14, v20
	v_mov_b32_e32 v15, v20
	v_mov_b32_e32 v16, v20
	v_mov_b32_e32 v17, v20
	v_mov_b32_e32 v18, v20
	v_mov_b32_e32 v19, v20
	v_mov_b32_e32 v36, v20
	v_mov_b32_e32 v37, v20
	v_mov_b32_e32 v38, v20
	v_mov_b32_e32 v39, v20
	v_mov_b32_e32 v40, v20
	v_mov_b32_e32 v41, v20
	v_mov_b32_e32 v42, v20
	v_mov_b32_e32 v43, v20
	v_mov_b32_e32 v52, v20
	v_mov_b32_e32 v53, v20
	v_mov_b32_e32 v54, v20
	v_mov_b32_e32 v55, v20
	v_mov_b32_e32 v56, v20
	v_mov_b32_e32 v57, v20
	v_mov_b32_e32 v58, v20
	v_mov_b32_e32 v59, v20
	v_mov_b32_e32 v60, v20
	v_mov_b32_e32 v61, v20
	v_mov_b32_e32 v62, v20
	v_mov_b32_e32 v63, v20
	v_mov_b32_e32 v64, v20
	v_mov_b32_e32 v65, v20
	v_mov_b32_e32 v66, v20
	v_mov_b32_e32 v67, v20
	v_mov_b32_e32 v68, v20
	v_mov_b32_e32 v69, v20
	v_mov_b32_e32 v70, v20
	v_mov_b32_e32 v71, v20
	v_mov_b32_e32 v76, v20
	v_mov_b32_e32 v77, v20
	v_mov_b32_e32 v78, v20
	v_mov_b32_e32 v79, v20
	v_mov_b32_e32 v80, v20
	v_mov_b32_e32 v81, v20
	v_mov_b32_e32 v82, v20
	v_mov_b32_e32 v83, v20
	v_mov_b32_e32 v92, v20
	v_mov_b32_e32 v93, v20
	v_mov_b32_e32 v94, v20
	v_mov_b32_e32 v95, v20
	v_mov_b32_e32 v96, v20
	v_mov_b32_e32 v97, v20
	v_mov_b32_e32 v98, v20
	v_mov_b32_e32 v99, v20
	v_mov_b32_e32 v108, v20
	v_mov_b32_e32 v109, v20
	v_mov_b32_e32 v110, v20
	v_mov_b32_e32 v111, v20
	v_mov_b32_e32 v112, v20
	v_mov_b32_e32 v113, v20
	v_mov_b32_e32 v114, v20
	v_mov_b32_e32 v115, v20
	v_mov_b32_e32 v72, v20
	v_mov_b32_e32 v73, v20
	v_mov_b32_e32 v74, v20
	v_mov_b32_e32 v75, v20
	v_mov_b32_e32 v84, v20
	v_mov_b32_e32 v85, v20
	v_mov_b32_e32 v86, v20
	v_mov_b32_e32 v87, v20
	v_mov_b32_e32 v88, v20
	v_mov_b32_e32 v89, v20
	v_mov_b32_e32 v90, v20
	v_mov_b32_e32 v91, v20
	v_mov_b32_e32 v100, v20
	v_mov_b32_e32 v101, v20
	v_mov_b32_e32 v102, v20
	v_mov_b32_e32 v103, v20
	v_mov_b32_e32 v104, v20
	v_mov_b32_e32 v105, v20
	v_mov_b32_e32 v106, v20
	v_mov_b32_e32 v107, v20
	v_mov_b32_e32 v116, v20
	v_mov_b32_e32 v117, v20
	v_mov_b32_e32 v118, v20
	v_mov_b32_e32 v119, v20
	v_mov_b32_e32 v120, v20
	v_mov_b32_e32 v121, v20
	v_mov_b32_e32 v122, v20
	v_mov_b32_e32 v123, v20
	v_mov_b32_e32 v124, v20
	v_mov_b32_e32 v125, v20
	v_mov_b32_e32 v126, v20
	v_mov_b32_e32 v127, v20
	v_mov_b32_e32 v28, v20
	v_mov_b32_e32 v29, v20
	v_mov_b32_e32 v30, v20
	v_mov_b32_e32 v31, v20
	v_mov_b32_e32 v32, v20
	v_mov_b32_e32 v33, v20
	v_mov_b32_e32 v34, v20
	v_mov_b32_e32 v35, v20
	v_mov_b32_e32 v8, v20
	v_mov_b32_e32 v9, v20
	v_mov_b32_e32 v10, v20
	v_mov_b32_e32 v11, v20
	v_mov_b32_e32 v4, v20
	v_mov_b32_e32 v5, v20
	v_mov_b32_e32 v6, v20
	v_mov_b32_e32 v7, v20
.LBB0_657:
	s_add_i32 s81, s76, 2
	s_add_u32 s78, s74, 0x80
	s_addc_u32 s77, s75, 0
	s_add_i32 s82, 0, 0x10000
	v_add_u32_e32 v140, s82, v189
	ds_read_b128 v[128:131], v140
	ds_read_b128 v[132:135], v140 offset:1024
	ds_read_b128 v[136:139], v140 offset:2048
	ds_read_b128 v[140:143], v140 offset:3072
	s_cmp_eq_u32 s67, s76
	s_cselect_b32 s76, s0, s78
	s_cselect_b32 s77, s1, s77
	s_cselect_b32 s79, s5, s80
	s_cselect_b32 s78, s4, s71
	v_lshl_add_u64 v[208:209], s[74:75], 0, v[204:205]
	s_add_i32 m0, s28, 0xc000
	ds_read_b128 v[144:147], v197
	ds_read_b128 v[148:151], v197 offset:1024
	ds_read_b128 v[152:155], v197 offset:2048
	ds_read_b128 v[156:159], v197 offset:3072
	ds_read_b128 v[160:163], v197 offset:4096
	ds_read_b128 v[164:167], v197 offset:5120
	ds_read_b128 v[168:171], v197 offset:6144
	ds_read_b128 v[172:175], v197 offset:7168
	global_load_lds_dwordx4 v[208:209], off
	v_lshl_add_u64 v[208:209], s[74:75], 0, v[206:207]
	s_add_i32 m0, s28, 0xe000
	s_nop 0
	global_load_lds_dwordx4 v[208:209], off
	s_waitcnt lgkmcnt(8)
	s_barrier
	s_waitcnt lgkmcnt(0)
	s_setprio 1
	s_waitcnt lgkmcnt(0)
	v_mfma_f32_16x16x32_bf16 v[124:127], v[128:131], v[144:147], v[124:127]
	v_mfma_f32_16x16x32_bf16 v[120:123], v[136:139], v[144:147], v[120:123]
	v_mfma_f32_16x16x32_bf16 v[116:119], v[128:131], v[152:155], v[116:119]
	v_mfma_f32_16x16x32_bf16 v[104:107], v[136:139], v[152:155], v[104:107]
	v_mfma_f32_16x16x32_bf16 v[100:103], v[128:131], v[160:163], v[100:103]
	v_mfma_f32_16x16x32_bf16 v[88:91], v[136:139], v[160:163], v[88:91]
	v_mfma_f32_16x16x32_bf16 v[84:87], v[128:131], v[168:171], v[84:87]
	v_mfma_f32_16x16x32_bf16 v[72:75], v[136:139], v[168:171], v[72:75]
	v_mfma_f32_16x16x32_bf16 v[124:127], v[132:135], v[148:151], v[124:127]
	v_mfma_f32_16x16x32_bf16 v[120:123], v[140:143], v[148:151], v[120:123]
	v_mfma_f32_16x16x32_bf16 v[116:119], v[132:135], v[156:159], v[116:119]
	v_mfma_f32_16x16x32_bf16 v[104:107], v[140:143], v[156:159], v[104:107]
	v_mfma_f32_16x16x32_bf16 v[100:103], v[132:135], v[164:167], v[100:103]
	v_mfma_f32_16x16x32_bf16 v[88:91], v[140:143], v[164:167], v[88:91]
	v_mfma_f32_16x16x32_bf16 v[84:87], v[132:135], v[172:175], v[84:87]
	v_mfma_f32_16x16x32_bf16 v[72:75], v[140:143], v[172:175], v[72:75]
	s_setprio 0
	s_barrier
; #define PG8_STAGE(bufoff, gbase, voff) do { _Pragma("unroll") for (int _i = 0; _i < 2; ++_i) \
;         __builtin_amdgcn_global_load_lds((const unsigned*)((const char*)(gbase) + (voff)[_i]), (LAS unsigned*)(lds + (bufoff) + ldsw + _i * 8192), 16, 0, 0); } while (0)
; #define PG8_LDA(dst, b, h) do { _Pragma("unroll") for (int m = 0; m < 4; ++m) _Pragma("unroll") for (int k = 0; k < 2; ++k) dst[m][k] = *(const LAS bf16x8*)(lds + PG8_SA(b, h) + aoff + m * 2048 + k * 1024); } while (0)
; #define PG8_LDB(dst, b, h) do { _Pragma("unroll") for (int n = 0; n < 2; ++n) _Pragma("unroll") for (int k = 0; k < 2; ++k) dst[n][k] = *(const LAS bf16x8*)(lds + PG8_SB(b, h) + boff + n * 2048 + k * 1024); } while (0)
; #define PG8_MMA(ai, bj, At, Bt) do { __builtin_amdgcn_s_setprio(1); _Pragma("unroll") for (int m = 0; m < 4; ++m) _Pragma("unroll") for (int n = 0; n < 2; ++n) _Pragma("unroll") for (int k = 0; k < 2; ++k) \
;         acc[ai][bj][m][n] = __builtin_amdgcn_mfma_f32_16x16x32_bf16(Bt[n][k], At[m][k], acc[ai][bj][m][n], 0, 0, 0); __builtin_amdgcn_s_setprio(0); } while (0)
; #define PG8_WAIT_V(n) asm volatile("s_waitcnt vmcnt(" #n ")" ::: "memory")
; #define PG8_WAIT_L(n) asm volatile("s_waitcnt lgkmcnt(" #n ")" ::: "memory")
; #define PG8_BAR __builtin_amdgcn_s_barrier()
; #define PG8_SCHED __builtin_amdgcn_sched_barrier(0)
; template <class F>
; DI void gemm_phase(const int tid, LAS unsigned char* lds, const bf16_t* Ap, int lda, const bf16_t* Bp, int ldb, int M, int N, int K, int G, int c, bool direct, const F& E) {
;     ...
;             PG8_LDB(B1, 0, 1); PG8_STAGE(PG8_SB(0, 0), b2, voffB);
;             PG8_BAR; PG8_WAIT_L(0); PG8_MMA(0, 1, At, B1); PG8_BAR;
;             PG8_LDA(At, 0, 1); PG8_STAGE(PG8_SA(0, 0), a2, voffA);
;             PG8_BAR; PG8_WAIT_L(0); PG8_MMA(1, 0, At, B0); PG8_BAR; PG8_SCHED;
;             PG8_STAGE(PG8_SB(0, 1), b2 + hsB, voffB);
;             PG8_WAIT_V(6); PG8_BAR; PG8_MMA(1, 1, At, B1); PG8_BAR;
;             PG8_LDB(B0, 1, 0); PG8_SCHED; PG8_LDA(At, 1, 0); PG8_STAGE(PG8_SA(0, 1), a2 + hsA, voffA);
;             PG8_WAIT_L(8); PG8_BAR; PG8_WAIT_L(0); PG8_MMA(0, 0, At, B0); PG8_BAR; PG8_SCHED;
	s_add_i32 s82, s82, s27
	v_add_u32_e32 v180, s95, v189
	v_lshl_add_u64 v[224:225], s[78:79], 0, v[178:179]
	s_mov_b32 m0, s82
	ds_read_b128 v[208:211], v180
	ds_read_b128 v[212:215], v180 offset:1024
	ds_read_b128 v[216:219], v180 offset:2048
	ds_read_b128 v[220:223], v180 offset:3072
	global_load_lds_dwordx4 v[224:225], off
	v_lshl_add_u64 v[226:227], s[78:79], 0, v[186:187]
	s_add_i32 m0, s82, 0x2000
	s_nop 0
	global_load_lds_dwordx4 v[226:227], off
	s_barrier
	s_waitcnt lgkmcnt(0)
	s_setprio 1
	s_waitcnt lgkmcnt(0)
	v_mfma_f32_16x16x32_bf16 v[112:115], v[208:211], v[144:147], v[112:115]
	v_mfma_f32_16x16x32_bf16 v[108:111], v[216:219], v[144:147], v[108:111]
	v_mfma_f32_16x16x32_bf16 v[96:99], v[208:211], v[152:155], v[96:99]
	v_mfma_f32_16x16x32_bf16 v[92:95], v[216:219], v[152:155], v[92:95]
	v_mfma_f32_16x16x32_bf16 v[80:83], v[208:211], v[160:163], v[80:83]
	v_mfma_f32_16x16x32_bf16 v[76:79], v[216:219], v[160:163], v[76:79]
	v_mfma_f32_16x16x32_bf16 v[68:71], v[208:211], v[168:171], v[68:71]
	v_mfma_f32_16x16x32_bf16 v[64:67], v[216:219], v[168:171], v[64:67]
	v_mfma_f32_16x16x32_bf16 v[112:115], v[212:215], v[148:151], v[112:115]
	v_mfma_f32_16x16x32_bf16 v[108:111], v[220:223], v[148:151], v[108:111]
	v_mfma_f32_16x16x32_bf16 v[96:99], v[212:215], v[156:159], v[96:99]
	v_mfma_f32_16x16x32_bf16 v[92:95], v[220:223], v[156:159], v[92:95]
	v_mfma_f32_16x16x32_bf16 v[80:83], v[212:215], v[164:167], v[80:83]
	v_mfma_f32_16x16x32_bf16 v[76:79], v[220:223], v[164:167], v[76:79]
	v_mfma_f32_16x16x32_bf16 v[68:71], v[212:215], v[172:175], v[68:71]
	v_mfma_f32_16x16x32_bf16 v[64:67], v[220:223], v[172:175], v[64:67]
	s_setprio 0
	s_mov_b32 m0, s28
	v_lshl_add_u64 v[228:229], s[76:77], 0, v[176:177]
	s_barrier
	ds_read_b128 v[144:147], v197 offset:16384
	ds_read_b128 v[148:151], v197 offset:17408
	ds_read_b128 v[152:155], v197 offset:18432
	ds_read_b128 v[156:159], v197 offset:19456
	ds_read_b128 v[160:163], v197 offset:20480
	ds_read_b128 v[164:167], v197 offset:21504
	ds_read_b128 v[168:171], v197 offset:22528
	ds_read_b128 v[172:175], v197 offset:23552
	global_load_lds_dwordx4 v[228:229], off
	v_lshl_add_u64 v[242:243], s[76:77], 0, v[184:185]
	s_mov_b32 m0, s34
	s_nop 0
	global_load_lds_dwordx4 v[242:243], off
	s_barrier
	s_waitcnt lgkmcnt(0)
	s_setprio 1
	s_waitcnt lgkmcnt(0)
	v_mfma_f32_16x16x32_bf16 v[60:63], v[128:131], v[144:147], v[60:63]
	v_mfma_f32_16x16x32_bf16 v[56:59], v[136:139], v[144:147], v[56:59]
	v_mfma_f32_16x16x32_bf16 v[52:55], v[128:131], v[152:155], v[52:55]
	v_mfma_f32_16x16x32_bf16 v[40:43], v[136:139], v[152:155], v[40:43]
	v_mfma_f32_16x16x32_bf16 v[36:39], v[128:131], v[160:163], v[36:39]
	v_mfma_f32_16x16x32_bf16 v[16:19], v[136:139], v[160:163], v[16:19]
	v_mfma_f32_16x16x32_bf16 v[12:15], v[128:131], v[168:171], v[12:15]
	v_mfma_f32_16x16x32_bf16 v[0:3], v[136:139], v[168:171], v[0:3]
	v_mfma_f32_16x16x32_bf16 v[60:63], v[132:135], v[148:151], v[60:63]
	v_mfma_f32_16x16x32_bf16 v[56:59], v[140:143], v[148:151], v[56:59]
	v_mfma_f32_16x16x32_bf16 v[52:55], v[132:135], v[156:159], v[52:55]
	v_mfma_f32_16x16x32_bf16 v[40:43], v[140:143], v[156:159], v[40:43]
	v_mfma_f32_16x16x32_bf16 v[36:39], v[132:135], v[164:167], v[36:39]
	v_mfma_f32_16x16x32_bf16 v[16:19], v[140:143], v[164:167], v[16:19]
	v_mfma_f32_16x16x32_bf16 v[12:15], v[132:135], v[172:175], v[12:15]
	v_mfma_f32_16x16x32_bf16 v[0:3], v[140:143], v[172:175], v[0:3]
	s_setprio 0
	s_barrier
	s_add_u32 s78, s78, s46
	s_addc_u32 s79, s79, 0
	s_add_i32 s82, s95, s27
	v_lshl_add_u64 v[244:245], s[78:79], 0, v[178:179]
	s_mov_b32 m0, s82
	v_lshl_add_u64 v[246:247], s[78:79], 0, v[186:187]
	global_load_lds_dwordx4 v[244:245], off
	s_add_i32 m0, s82, 0x2000
	s_nop 0
	global_load_lds_dwordx4 v[246:247], off
	s_waitcnt vmcnt(6)
	s_barrier
	s_setprio 1
	v_mfma_f32_16x16x32_bf16 v[48:51], v[208:211], v[144:147], v[48:51]
	v_mfma_f32_16x16x32_bf16 v[44:47], v[216:219], v[144:147], v[44:47]
	v_mfma_f32_16x16x32_bf16 v[24:27], v[208:211], v[152:155], v[24:27]
	v_mfma_f32_16x16x32_bf16 v[20:23], v[216:219], v[152:155], v[20:23]
	v_mfma_f32_16x16x32_bf16 v[28:31], v[208:211], v[160:163], v[28:31]
	v_mfma_f32_16x16x32_bf16 v[32:35], v[216:219], v[160:163], v[32:35]
	v_mfma_f32_16x16x32_bf16 v[8:11], v[208:211], v[168:171], v[8:11]
	v_mfma_f32_16x16x32_bf16 v[4:7], v[216:219], v[168:171], v[4:7]
	v_mfma_f32_16x16x32_bf16 v[48:51], v[212:215], v[148:151], v[48:51]
	v_mfma_f32_16x16x32_bf16 v[44:47], v[220:223], v[148:151], v[44:47]
	v_mfma_f32_16x16x32_bf16 v[24:27], v[212:215], v[156:159], v[24:27]
	v_mfma_f32_16x16x32_bf16 v[20:23], v[220:223], v[156:159], v[20:23]
	v_mfma_f32_16x16x32_bf16 v[28:31], v[212:215], v[164:167], v[28:31]
	v_mfma_f32_16x16x32_bf16 v[32:35], v[220:223], v[164:167], v[32:35]
	v_mfma_f32_16x16x32_bf16 v[8:11], v[212:215], v[172:175], v[8:11]
	v_mfma_f32_16x16x32_bf16 v[4:7], v[220:223], v[172:175], v[4:7]
	s_setprio 0
	s_add_i32 s78, 0, 0x18000
	v_add_u32_e32 v140, s78, v189
	s_barrier
	ds_read_b128 v[128:131], v140
	ds_read_b128 v[132:135], v140 offset:1024
	ds_read_b128 v[136:139], v140 offset:2048
	ds_read_b128 v[140:143], v140 offset:3072
	s_add_u32 s76, s76, s24
	s_addc_u32 s77, s77, 0
	s_mov_b32 m0, s60
	v_lshl_add_u64 v[208:209], s[76:77], 0, v[176:177]
	ds_read_b128 v[144:147], v197 offset:32768
	ds_read_b128 v[148:151], v197 offset:33792
	ds_read_b128 v[152:155], v197 offset:34816
	ds_read_b128 v[156:159], v197 offset:35840
	ds_read_b128 v[160:163], v197 offset:36864
	ds_read_b128 v[164:167], v197 offset:37888
	ds_read_b128 v[168:171], v197 offset:38912
	ds_read_b128 v[172:175], v197 offset:39936
	global_load_lds_dwordx4 v[208:209], off
	v_lshl_add_u64 v[208:209], s[76:77], 0, v[184:185]
	s_mov_b32 m0, s61
	s_nop 0
	global_load_lds_dwordx4 v[208:209], off
	s_waitcnt lgkmcnt(8)
	s_barrier
; #define PG8_STAGE(bufoff, gbase, voff) do { _Pragma("unroll") for (int _i = 0; _i < 2; ++_i) \
;         __builtin_amdgcn_global_load_lds((const unsigned*)((const char*)(gbase) + (voff)[_i]), (LAS unsigned*)(lds + (bufoff) + ldsw + _i * 8192), 16, 0, 0); } while (0)
; #define PG8_LDA(dst, b, h) do { _Pragma("unroll") for (int m = 0; m < 4; ++m) _Pragma("unroll") for (int k = 0; k < 2; ++k) dst[m][k] = *(const LAS bf16x8*)(lds + PG8_SA(b, h) + aoff + m * 2048 + k * 1024); } while (0)
; #define PG8_LDB(dst, b, h) do { _Pragma("unroll") for (int n = 0; n < 2; ++n) _Pragma("unroll") for (int k = 0; k < 2; ++k) dst[n][k] = *(const LAS bf16x8*)(lds + PG8_SB(b, h) + boff + n * 2048 + k * 1024); } while (0)
; #define PG8_MMA(ai, bj, At, Bt) do { __builtin_amdgcn_s_setprio(1); _Pragma("unroll") for (int m = 0; m < 4; ++m) _Pragma("unroll") for (int n = 0; n < 2; ++n) _Pragma("unroll") for (int k = 0; k < 2; ++k) \
;         acc[ai][bj][m][n] = __builtin_amdgcn_mfma_f32_16x16x32_bf16(Bt[n][k], At[m][k], acc[ai][bj][m][n], 0, 0, 0); __builtin_amdgcn_s_setprio(0); } while (0)
; #define PG8_WAIT_V(n) asm volatile("s_waitcnt vmcnt(" #n ")" ::: "memory")
; #define PG8_WAIT_L(n) asm volatile("s_waitcnt lgkmcnt(" #n ")" ::: "memory")
; #define PG8_BAR __builtin_amdgcn_s_barrier()
; #define PG8_SCHED __builtin_amdgcn_sched_barrier(0)
; template <class F>
; DI void gemm_phase(const int tid, LAS unsigned char* lds, const bf16_t* Ap, int lda, const bf16_t* Bp, int ldb, int M, int N, int K, int G, int c, bool direct, const F& E) {
;     ...
;             PG8_WAIT_L(8); PG8_BAR; PG8_WAIT_L(0); PG8_MMA(0, 0, At, B0); PG8_BAR; PG8_SCHED;
;             PG8_LDB(B1, 1, 1); PG8_STAGE(PG8_SB(1, 0), b3, voffB);
;             PG8_BAR; PG8_WAIT_L(0); PG8_MMA(0, 1, At, B1); PG8_BAR;
;             PG8_LDA(At, 1, 1); PG8_STAGE(PG8_SA(1, 0), a3, voffA);
;             PG8_BAR; PG8_WAIT_L(0); PG8_MMA(1, 0, At, B0); PG8_BAR; PG8_SCHED;
;             PG8_STAGE(PG8_SB(1, 1), b3 + hsB, voffB);
;             PG8_WAIT_V(6); PG8_BAR; PG8_MMA(1, 1, At, B1); PG8_BAR;
	s_waitcnt lgkmcnt(0)
	s_setprio 1
	s_waitcnt lgkmcnt(0)
	v_mfma_f32_16x16x32_bf16 v[124:127], v[128:131], v[144:147], v[124:127]
	v_mfma_f32_16x16x32_bf16 v[120:123], v[136:139], v[144:147], v[120:123]
	v_mfma_f32_16x16x32_bf16 v[116:119], v[128:131], v[152:155], v[116:119]
	v_mfma_f32_16x16x32_bf16 v[104:107], v[136:139], v[152:155], v[104:107]
	v_mfma_f32_16x16x32_bf16 v[100:103], v[128:131], v[160:163], v[100:103]
	v_mfma_f32_16x16x32_bf16 v[88:91], v[136:139], v[160:163], v[88:91]
	v_mfma_f32_16x16x32_bf16 v[84:87], v[128:131], v[168:171], v[84:87]
	v_mfma_f32_16x16x32_bf16 v[72:75], v[136:139], v[168:171], v[72:75]
	v_mfma_f32_16x16x32_bf16 v[124:127], v[132:135], v[148:151], v[124:127]
	v_mfma_f32_16x16x32_bf16 v[120:123], v[140:143], v[148:151], v[120:123]
	v_mfma_f32_16x16x32_bf16 v[116:119], v[132:135], v[156:159], v[116:119]
	v_mfma_f32_16x16x32_bf16 v[104:107], v[140:143], v[156:159], v[104:107]
	v_mfma_f32_16x16x32_bf16 v[100:103], v[132:135], v[164:167], v[100:103]
	v_mfma_f32_16x16x32_bf16 v[88:91], v[140:143], v[164:167], v[88:91]
	v_mfma_f32_16x16x32_bf16 v[84:87], v[132:135], v[172:175], v[84:87]
	v_mfma_f32_16x16x32_bf16 v[72:75], v[140:143], v[172:175], v[72:75]
	s_setprio 0
	s_barrier
	s_add_i32 s76, 0, 0x1c000
	s_add_i32 s77, s78, s27
	v_add_u32_e32 v180, s76, v189
	v_lshl_add_u64 v[224:225], v[224:225], 0, s[30:31]
	s_mov_b32 m0, s77
	ds_read_b128 v[208:211], v180
	ds_read_b128 v[212:215], v180 offset:1024
	ds_read_b128 v[216:219], v180 offset:2048
	ds_read_b128 v[220:223], v180 offset:3072
	global_load_lds_dwordx4 v[224:225], off
	v_lshl_add_u64 v[224:225], v[226:227], 0, s[30:31]
	s_add_i32 m0, s77, 0x2000
	s_nop 0
	global_load_lds_dwordx4 v[224:225], off
	s_barrier
	s_waitcnt lgkmcnt(0)
	s_setprio 1
	s_waitcnt lgkmcnt(0)
	v_mfma_f32_16x16x32_bf16 v[112:115], v[208:211], v[144:147], v[112:115]
	v_mfma_f32_16x16x32_bf16 v[108:111], v[216:219], v[144:147], v[108:111]
	v_mfma_f32_16x16x32_bf16 v[96:99], v[208:211], v[152:155], v[96:99]
	v_mfma_f32_16x16x32_bf16 v[92:95], v[216:219], v[152:155], v[92:95]
	v_mfma_f32_16x16x32_bf16 v[80:83], v[208:211], v[160:163], v[80:83]
	v_mfma_f32_16x16x32_bf16 v[76:79], v[216:219], v[160:163], v[76:79]
	v_mfma_f32_16x16x32_bf16 v[68:71], v[208:211], v[168:171], v[68:71]
	v_mfma_f32_16x16x32_bf16 v[64:67], v[216:219], v[168:171], v[64:67]
	v_mfma_f32_16x16x32_bf16 v[112:115], v[212:215], v[148:151], v[112:115]
	v_mfma_f32_16x16x32_bf16 v[108:111], v[220:223], v[148:151], v[108:111]
	v_mfma_f32_16x16x32_bf16 v[96:99], v[212:215], v[156:159], v[96:99]
	v_mfma_f32_16x16x32_bf16 v[92:95], v[220:223], v[156:159], v[92:95]
	v_mfma_f32_16x16x32_bf16 v[80:83], v[212:215], v[164:167], v[80:83]
	v_mfma_f32_16x16x32_bf16 v[76:79], v[220:223], v[164:167], v[76:79]
	v_mfma_f32_16x16x32_bf16 v[68:71], v[212:215], v[172:175], v[68:71]
	v_mfma_f32_16x16x32_bf16 v[64:67], v[220:223], v[172:175], v[64:67]
	s_setprio 0
	s_mov_b32 m0, s62
	v_lshl_add_u64 v[224:225], v[228:229], 0, s[30:31]
	s_barrier
	ds_read_b128 v[144:147], v197 offset:49152
	ds_read_b128 v[148:151], v197 offset:50176
	ds_read_b128 v[152:155], v197 offset:51200
	ds_read_b128 v[156:159], v197 offset:52224
	ds_read_b128 v[160:163], v197 offset:53248
	ds_read_b128 v[164:167], v197 offset:54272
	ds_read_b128 v[168:171], v197 offset:55296
	ds_read_b128 v[172:175], v197 offset:56320
	global_load_lds_dwordx4 v[224:225], off
	v_lshl_add_u64 v[224:225], v[242:243], 0, s[30:31]
	s_mov_b32 m0, s63
	s_nop 0
	global_load_lds_dwordx4 v[224:225], off
	s_barrier
	s_waitcnt lgkmcnt(0)
	s_setprio 1
	s_waitcnt lgkmcnt(0)
	v_mfma_f32_16x16x32_bf16 v[60:63], v[128:131], v[144:147], v[60:63]
	v_mfma_f32_16x16x32_bf16 v[56:59], v[136:139], v[144:147], v[56:59]
	v_mfma_f32_16x16x32_bf16 v[52:55], v[128:131], v[152:155], v[52:55]
	v_mfma_f32_16x16x32_bf16 v[40:43], v[136:139], v[152:155], v[40:43]
	v_mfma_f32_16x16x32_bf16 v[36:39], v[128:131], v[160:163], v[36:39]
	v_mfma_f32_16x16x32_bf16 v[16:19], v[136:139], v[160:163], v[16:19]
	v_mfma_f32_16x16x32_bf16 v[12:15], v[128:131], v[168:171], v[12:15]
	v_mfma_f32_16x16x32_bf16 v[0:3], v[136:139], v[168:171], v[0:3]
	v_mfma_f32_16x16x32_bf16 v[60:63], v[132:135], v[148:151], v[60:63]
	v_mfma_f32_16x16x32_bf16 v[56:59], v[140:143], v[148:151], v[56:59]
	v_mfma_f32_16x16x32_bf16 v[52:55], v[132:135], v[156:159], v[52:55]
	v_mfma_f32_16x16x32_bf16 v[40:43], v[140:143], v[156:159], v[40:43]
	v_mfma_f32_16x16x32_bf16 v[36:39], v[132:135], v[164:167], v[36:39]
	v_mfma_f32_16x16x32_bf16 v[16:19], v[140:143], v[164:167], v[16:19]
	v_mfma_f32_16x16x32_bf16 v[12:15], v[132:135], v[172:175], v[12:15]
	v_mfma_f32_16x16x32_bf16 v[0:3], v[140:143], v[172:175], v[0:3]
	s_setprio 0
	s_barrier
	s_add_i32 s76, s76, s27
	v_lshl_add_u64 v[128:129], v[244:245], 0, s[30:31]
	s_mov_b32 m0, s76
	s_nop 0
	global_load_lds_dwordx4 v[128:129], off
	v_lshl_add_u64 v[128:129], v[246:247], 0, s[30:31]
	s_add_i32 m0, s76, 0x2000
	s_nop 0
	global_load_lds_dwordx4 v[128:129], off
	s_waitcnt vmcnt(6)
	s_barrier
	s_setprio 1
	v_mfma_f32_16x16x32_bf16 v[48:51], v[208:211], v[144:147], v[48:51]
	v_mfma_f32_16x16x32_bf16 v[44:47], v[216:219], v[144:147], v[44:47]
	v_mfma_f32_16x16x32_bf16 v[24:27], v[208:211], v[152:155], v[24:27]
	v_mfma_f32_16x16x32_bf16 v[20:23], v[216:219], v[152:155], v[20:23]
	v_mfma_f32_16x16x32_bf16 v[28:31], v[208:211], v[160:163], v[28:31]
	v_mfma_f32_16x16x32_bf16 v[32:35], v[216:219], v[160:163], v[32:35]
	v_mfma_f32_16x16x32_bf16 v[8:11], v[208:211], v[168:171], v[8:11]
	v_mfma_f32_16x16x32_bf16 v[4:7], v[216:219], v[168:171], v[4:7]
	v_mfma_f32_16x16x32_bf16 v[48:51], v[212:215], v[148:151], v[48:51]
	v_mfma_f32_16x16x32_bf16 v[44:47], v[220:223], v[148:151], v[44:47]
	v_mfma_f32_16x16x32_bf16 v[24:27], v[212:215], v[156:159], v[24:27]
	v_mfma_f32_16x16x32_bf16 v[20:23], v[220:223], v[156:159], v[20:23]
	v_mfma_f32_16x16x32_bf16 v[28:31], v[212:215], v[164:167], v[28:31]
	v_mfma_f32_16x16x32_bf16 v[32:35], v[220:223], v[164:167], v[32:35]
	v_mfma_f32_16x16x32_bf16 v[8:11], v[212:215], v[172:175], v[8:11]
	v_mfma_f32_16x16x32_bf16 v[4:7], v[220:223], v[172:175], v[4:7]
	s_setprio 0
	s_add_u32 s74, s74, 0x100
	s_addc_u32 s75, s75, 0
	s_add_u32 s71, s71, 0x100
	s_addc_u32 s80, s80, 0
	s_cmp_ge_u32 s81, s26
	s_mov_b32 s76, s81
	s_barrier
; #define PG8_WAIT_V(n) asm volatile("s_waitcnt vmcnt(" #n ")" ::: "memory")
; template <class F>
; DI void gemm_phase(const int tid, LAS unsigned char* lds, const bf16_t* Ap, int lda, const bf16_t* Bp, int ldb, int M, int N, int K, int G, int c, bool direct, const F& E) {
;     ...
;             PG8_WAIT_V(6); PG8_BAR; PG8_MMA(1, 1, At, B1); PG8_BAR;
;         }
;         if (E.kind == 7  ) E.fused(acc, cur.pm, cur.pn, wr, wc, fr, fq);
; DI void Epi::fused(const f32x4 (&acc)[2][2][4][2], int pm, int pn, int wr, int wc, int fr, int fq) const {
;     const Epi& E = *this;
; #pragma unroll
;     for (int bj = 0; bj < 2; ++bj) {
;         const int ncol = pn * 256 + bj * 128 + wc * 32 + 8 * fq, j0 = (ncol >> 3) * 4;
;         const f32x4 wa0 = *(const f32x4*)(E.cf0 + j0), wa1 = *(const f32x4*)(E.cf0 + FF2 + j0), wa2 = *(const f32x4*)(E.cf0 + 2 * FF2 + j0);
;         const f32x4 wb0 = *(const f32x4*)(E.cf0 + FFH + j0), wb1 = *(const f32x4*)(E.cf0 + FF2 + FFH + j0), wb2 = *(const f32x4*)(E.cf0 + 2 * FF2 + FFH + j0);
;         const f32x4 ba = *(const f32x4*)(E.cf1 + j0), bb = *(const f32x4*)(E.cf1 + FFH + j0);
; #pragma unroll
;         for (int ai = 0; ai < 2; ++ai) {
;             f32x4 pa = (f32x4){0.f, 0.f, 0.f, 0.f}, pb = pa;
; #pragma unroll
;             for (int m = 0; m < 4; ++m) {
;                 const f32x4 ca = acc[ai][bj][m][0], cb = acc[ai][bj][m][1];
;                 const int row = pm * 256 + ai * 128 + wr * 64 + m * 16 + fr;
;                 float o[4];
; #pragma unroll
;                 for (int e = 0; e < 4; ++e) {
;                     const float a1 = dppf<0x111>(ca[e]) + dppf<0x10F>(pa[e]), a2 = dppf<0x112>(ca[e]) + dppf<0x10E>(pa[e]);
;                     const float b1 = dppf<0x111>(cb[e]) + dppf<0x10F>(pb[e]), b2 = dppf<0x112>(cb[e]) + dppf<0x10E>(pb[e]);
;                     const float ya = fmaf(wa0[e], a2, fmaf(wa1[e], a1, fmaf(wa2[e], ca[e], ba[e])));
;                     const float yb = fmaf(wb0[e], b2, fmaf(wb1[e], b1, fmaf(wb2[e], cb[e], bb[e])));
;                     o[e] = silu_fast(ya) * yb; }
;                 if (m > 0 || fr >= 2) { u32x2 w; w.x = pk2(o[0], o[1]); w.y = pk2(o[2], o[3]); *(u32x2*)(E.d0 + (size_t)row * FFH + j0) = w; }
;                 if ((m == 0 && fr < 2) || (m == 3 && fr >= 14)) { float* hb = E.f0 + ((size_t)(row >> 6) * 4 + (m == 0 ? fr : fr - 12)) * FF2 + ncol; *(f32x4*)hb = ca; *(f32x4*)(hb + 4) = cb; }
	s_cbranch_scc0 .LBB0_657
	s_mov_b64 s[76:77], -1
	s_mov_b64 s[74:75], 0
	s_cmp_lt_i32 s92, 3
	s_mov_b64 s[78:79], 0
	s_cbranch_scc1 .LBB0_688
	s_cmp_gt_i32 s92, 6
	s_mov_b64 s[78:79], -1
	s_cbranch_scc0 .LBB0_685
	v_lshl_or_b32 v240, s70, 8, v194
	v_mov_b32_e32 v241, 0
	s_lshl_b32 s71, s36, 8
	v_readlane_b32 s76, v255, 16
	s_nop 3
	s_add_i32 s71, s71, s76
	v_or_b32_e32 v199, s71, v188
	v_lshlrev_b32_e32 v238, 1, v240
	v_mov_b32_e32 v239, 0
	v_lshl_add_u64 v[136:137], s[22:23], 0, v[238:239]
	global_load_dwordx4 v[136:139], v[136:137], off
	v_readlane_b32 s76, v254, 54
	v_readlane_b32 s77, v254, 55
	s_nop 1
	v_lshl_add_u64 v[140:141], s[76:77], 0, v[238:239]
	global_load_dwordx4 v[140:143], v[140:141], off
	v_readlane_b32 s76, v254, 56
	v_readlane_b32 s77, v254, 57
	s_nop 1
	v_lshl_add_u64 v[152:153], s[76:77], 0, v[238:239]
	global_load_dwordx4 v[152:155], v[152:153], off
	v_readlane_b32 s76, v255, 4
	v_readlane_b32 s77, v255, 5
	s_nop 1
	v_lshl_add_u64 v[128:129], s[76:77], 0, v[238:239]
	global_load_dwordx4 v[128:131], v[128:129], off
	v_readlane_b32 s76, v255, 6
	v_readlane_b32 s77, v255, 7
	s_nop 1
	v_lshl_add_u64 v[132:133], s[76:77], 0, v[238:239]
	global_load_dwordx4 v[132:135], v[132:133], off
	v_readlane_b32 s76, v255, 8
	v_readlane_b32 s77, v255, 9
	s_nop 1
	v_lshl_add_u64 v[144:145], s[76:77], 0, v[238:239]
	global_load_dwordx4 v[144:147], v[144:145], off
	v_readlane_b32 s76, v254, 49
	v_readlane_b32 s77, v254, 50
	s_nop 1
	v_lshl_add_u64 v[156:157], s[76:77], 0, v[238:239]
	global_load_dwordx4 v[156:159], v[156:157], off
	v_lshl_add_u64 v[148:149], s[72:73], 0, v[238:239]
	global_load_dwordx4 v[148:151], v[148:149], off
	v_mov_b32_e32 v228, v199
	v_mov_b64_e32 v[224:225], s[12:13]
	s_movk_i32 s80, 0x1600
	v_mad_i64_i32 v[224:225], s[78:79], v228, s80, v[224:225]
	v_mov_b32_e32 v228, v240
	v_mov_b32_e32 v229, 0
	v_lshl_add_u64 v[224:225], v[228:229], 0, v[224:225]
	s_waitcnt vmcnt(0)
	v_fma_f32 v160, v152, v124, v156
	v_fma_f32 v161, v153, v125, v157
	v_fma_f32 v162, v154, v126, v158
	v_fma_f32 v163, v155, v127, v159
	v_fma_f32 v164, v144, v120, v148
	v_fma_f32 v165, v145, v121, v149
	v_fma_f32 v166, v146, v122, v150
	v_fma_f32 v167, v147, v123, v151
	v_fmac_f32_dpp v160, v124, v140 row_shr:1 row_mask:0xf bank_mask:0xf
	v_fmac_f32_dpp v161, v125, v141 row_shr:1 row_mask:0xf bank_mask:0xf
	v_fmac_f32_dpp v162, v126, v142 row_shr:1 row_mask:0xf bank_mask:0xf
	v_fmac_f32_dpp v163, v127, v143 row_shr:1 row_mask:0xf bank_mask:0xf
	v_fmac_f32_dpp v164, v120, v132 row_shr:1 row_mask:0xf bank_mask:0xf
	v_fmac_f32_dpp v165, v121, v133 row_shr:1 row_mask:0xf bank_mask:0xf
	v_fmac_f32_dpp v166, v122, v134 row_shr:1 row_mask:0xf bank_mask:0xf
	v_fmac_f32_dpp v167, v123, v135 row_shr:1 row_mask:0xf bank_mask:0xf
	v_fmac_f32_dpp v160, v124, v136 row_shr:2 row_mask:0xf bank_mask:0xf
	v_fmac_f32_dpp v161, v125, v137 row_shr:2 row_mask:0xf bank_mask:0xf
	v_fmac_f32_dpp v162, v126, v138 row_shr:2 row_mask:0xf bank_mask:0xf
	v_fmac_f32_dpp v163, v127, v139 row_shr:2 row_mask:0xf bank_mask:0xf
	v_fmac_f32_dpp v164, v120, v128 row_shr:2 row_mask:0xf bank_mask:0xf
	v_fmac_f32_dpp v165, v121, v129 row_shr:2 row_mask:0xf bank_mask:0xf
	v_fmac_f32_dpp v166, v122, v130 row_shr:2 row_mask:0xf bank_mask:0xf
	v_fmac_f32_dpp v167, v123, v131 row_shr:2 row_mask:0xf bank_mask:0xf
	v_mul_f32_e32 v168, 0xbfb8aa3b, v160
	v_mul_f32_e32 v169, 0xbfb8aa3b, v161
	v_mul_f32_e32 v170, 0xbfb8aa3b, v162
	v_mul_f32_e32 v171, 0xbfb8aa3b, v163
	v_exp_f32_e32 v168, v168
	v_exp_f32_e32 v169, v169
	v_exp_f32_e32 v170, v170
	v_exp_f32_e32 v171, v171
	v_add_f32_e32 v168, 1.0, v168
	v_add_f32_e32 v169, 1.0, v169
	v_add_f32_e32 v170, 1.0, v170
	v_add_f32_e32 v171, 1.0, v171
	v_rcp_f32_e32 v168, v168
	v_rcp_f32_e32 v169, v169
	v_rcp_f32_e32 v170, v170
	v_rcp_f32_e32 v171, v171
	v_mov_b64_e32 v[174:175], v[224:225]
	v_mul_f32_e32 v160, v160, v168
	v_mul_f32_e32 v161, v161, v169
	v_mul_f32_e32 v162, v162, v170
	v_mul_f32_e32 v163, v163, v171
	v_mul_f32_e32 v160, v164, v160
	v_mul_f32_e32 v161, v165, v161
	v_mul_f32_e32 v162, v166, v162
	v_mul_f32_e32 v163, v167, v163
	v_cvt_pk_bf16_f32 v172, v160, v161
	v_cvt_pk_bf16_f32 v173, v162, v163
	s_and_saveexec_b64 s[76:77], s[38:39]
	global_store_dwordx2 v[174:175], v[172:173], off
	s_or_b64 exec, exec, s[76:77]
	s_ashr_i32 s80, s71, 6
	s_lshl_b32 s80, s80, 2
	v_add_u32_e32 v226, s80, v188
	v_mov_b64_e32 v[174:175], s[8:9]
	s_movk_i32 s80, 0x5800
	v_mad_i64_i32 v[174:175], s[78:79], v226, s80, v[174:175]
	v_lshl_add_u64 v[174:175], v[228:229], 2, v[174:175]
	s_and_saveexec_b64 s[76:77], s[40:41]
	global_store_dwordx4 v[174:175], v[124:127], off
	global_store_dwordx4 v[174:175], v[120:123], off offset:16
	s_or_b64 exec, exec, s[76:77]
	v_fma_f32 v208, v152, v116, v156
	v_fma_f32 v209, v153, v117, v157
	v_fma_f32 v210, v154, v118, v158
	v_fma_f32 v211, v155, v119, v159
	v_fma_f32 v212, v144, v104, v148
	v_fma_f32 v213, v145, v105, v149
	v_fma_f32 v214, v146, v106, v150
	v_fma_f32 v215, v147, v107, v151
	v_fmac_f32_dpp v208, v116, v140 row_shr:1 row_mask:0xf bank_mask:0xf
	v_fmac_f32_dpp v209, v117, v141 row_shr:1 row_mask:0xf bank_mask:0xf
	v_fmac_f32_dpp v210, v118, v142 row_shr:1 row_mask:0xf bank_mask:0xf
	v_fmac_f32_dpp v211, v119, v143 row_shr:1 row_mask:0xf bank_mask:0xf
	v_fmac_f32_dpp v212, v104, v132 row_shr:1 row_mask:0xf bank_mask:0xf
	v_fmac_f32_dpp v213, v105, v133 row_shr:1 row_mask:0xf bank_mask:0xf
	v_fmac_f32_dpp v214, v106, v134 row_shr:1 row_mask:0xf bank_mask:0xf
	v_fmac_f32_dpp v215, v107, v135 row_shr:1 row_mask:0xf bank_mask:0xf
	v_fmac_f32_dpp v208, v124, v140 row_shl:15 row_mask:0xf bank_mask:0xf
; DI float silu_fast(float x) { return x * __builtin_amdgcn_rcpf(1.f + __expf(-x)); }
; template <int CTRL> DI float dppf(float v) { return __builtin_bit_cast(float, __builtin_amdgcn_update_dpp(0, __builtin_bit_cast(int, v), CTRL, 0xf, 0xf, true)); }
; DI void Epi::fused(const f32x4 (&acc)[2][2][4][2], int pm, int pn, int wr, int wc, int fr, int fq) const {
;     ...
;             for (int m = 0; m < 4; ++m) {
;                 const f32x4 ca = acc[ai][bj][m][0], cb = acc[ai][bj][m][1];
;                 const int row = pm * 256 + ai * 128 + wr * 64 + m * 16 + fr;
;                 float o[4];
; #pragma unroll
;                 for (int e = 0; e < 4; ++e) {
;                     const float a1 = dppf<0x111>(ca[e]) + dppf<0x10F>(pa[e]), a2 = dppf<0x112>(ca[e]) + dppf<0x10E>(pa[e]);
;                     const float b1 = dppf<0x111>(cb[e]) + dppf<0x10F>(pb[e]), b2 = dppf<0x112>(cb[e]) + dppf<0x10E>(pb[e]);
;                     const float ya = fmaf(wa0[e], a2, fmaf(wa1[e], a1, fmaf(wa2[e], ca[e], ba[e])));
;                     const float yb = fmaf(wb0[e], b2, fmaf(wb1[e], b1, fmaf(wb2[e], cb[e], bb[e])));
;                     o[e] = silu_fast(ya) * yb; }
;                 if (m > 0 || fr >= 2) { u32x2 w; w.x = pk2(o[0], o[1]); w.y = pk2(o[2], o[3]); *(u32x2*)(E.d0 + (size_t)row * FFH + j0) = w; }
	v_fmac_f32_dpp v209, v125, v141 row_shl:15 row_mask:0xf bank_mask:0xf
	v_fmac_f32_dpp v210, v126, v142 row_shl:15 row_mask:0xf bank_mask:0xf
	v_fmac_f32_dpp v211, v127, v143 row_shl:15 row_mask:0xf bank_mask:0xf
	v_fmac_f32_dpp v212, v120, v132 row_shl:15 row_mask:0xf bank_mask:0xf
	v_fmac_f32_dpp v213, v121, v133 row_shl:15 row_mask:0xf bank_mask:0xf
	v_fmac_f32_dpp v214, v122, v134 row_shl:15 row_mask:0xf bank_mask:0xf
	v_fmac_f32_dpp v215, v123, v135 row_shl:15 row_mask:0xf bank_mask:0xf
	v_fmac_f32_dpp v208, v116, v136 row_shr:2 row_mask:0xf bank_mask:0xf
	v_fmac_f32_dpp v209, v117, v137 row_shr:2 row_mask:0xf bank_mask:0xf
	v_fmac_f32_dpp v210, v118, v138 row_shr:2 row_mask:0xf bank_mask:0xf
	v_fmac_f32_dpp v211, v119, v139 row_shr:2 row_mask:0xf bank_mask:0xf
	v_fmac_f32_dpp v212, v104, v128 row_shr:2 row_mask:0xf bank_mask:0xf
	v_fmac_f32_dpp v213, v105, v129 row_shr:2 row_mask:0xf bank_mask:0xf
	v_fmac_f32_dpp v214, v106, v130 row_shr:2 row_mask:0xf bank_mask:0xf
	v_fmac_f32_dpp v215, v107, v131 row_shr:2 row_mask:0xf bank_mask:0xf
	v_fmac_f32_dpp v208, v124, v136 row_shl:14 row_mask:0xf bank_mask:0xf
	v_fmac_f32_dpp v209, v125, v137 row_shl:14 row_mask:0xf bank_mask:0xf
	v_fmac_f32_dpp v210, v126, v138 row_shl:14 row_mask:0xf bank_mask:0xf
	v_fmac_f32_dpp v211, v127, v139 row_shl:14 row_mask:0xf bank_mask:0xf
	v_fmac_f32_dpp v212, v120, v128 row_shl:14 row_mask:0xf bank_mask:0xf
	v_fmac_f32_dpp v213, v121, v129 row_shl:14 row_mask:0xf bank_mask:0xf
	v_fmac_f32_dpp v214, v122, v130 row_shl:14 row_mask:0xf bank_mask:0xf
	v_fmac_f32_dpp v215, v123, v131 row_shl:14 row_mask:0xf bank_mask:0xf
	v_mul_f32_e32 v216, 0xbfb8aa3b, v208
	v_mul_f32_e32 v217, 0xbfb8aa3b, v209
	v_mul_f32_e32 v218, 0xbfb8aa3b, v210
	v_mul_f32_e32 v219, 0xbfb8aa3b, v211
	v_exp_f32_e32 v216, v216
	v_exp_f32_e32 v217, v217
	v_exp_f32_e32 v218, v218
	v_exp_f32_e32 v219, v219
	v_add_f32_e32 v216, 1.0, v216
	v_add_f32_e32 v217, 1.0, v217
	v_add_f32_e32 v218, 1.0, v218
	v_add_f32_e32 v219, 1.0, v219
	v_rcp_f32_e32 v216, v216
	v_rcp_f32_e32 v217, v217
	v_rcp_f32_e32 v218, v218
	v_rcp_f32_e32 v219, v219
	s_mov_b32 s80, 0x16000
	s_mov_b32 s81, 0
	v_lshl_add_u64 v[222:223], v[224:225], 0, s[80:81]
	v_mul_f32_e32 v208, v208, v216
	v_mul_f32_e32 v209, v209, v217
	v_mul_f32_e32 v210, v210, v218
	v_mul_f32_e32 v211, v211, v219
	v_mul_f32_e32 v208, v212, v208
	v_mul_f32_e32 v209, v213, v209
	v_mul_f32_e32 v210, v214, v210
	v_mul_f32_e32 v211, v215, v211
	v_cvt_pk_bf16_f32 v220, v208, v209
	v_cvt_pk_bf16_f32 v221, v210, v211
	global_store_dwordx2 v[222:223], v[220:221], off
	v_fma_f32 v160, v152, v100, v156
	v_fma_f32 v161, v153, v101, v157
	v_fma_f32 v162, v154, v102, v158
	v_fma_f32 v163, v155, v103, v159
	v_fma_f32 v164, v144, v88, v148
	v_fma_f32 v165, v145, v89, v149
	v_fma_f32 v166, v146, v90, v150
	v_fma_f32 v167, v147, v91, v151
	v_fmac_f32_dpp v160, v100, v140 row_shr:1 row_mask:0xf bank_mask:0xf
	v_fmac_f32_dpp v161, v101, v141 row_shr:1 row_mask:0xf bank_mask:0xf
	v_fmac_f32_dpp v162, v102, v142 row_shr:1 row_mask:0xf bank_mask:0xf
	v_fmac_f32_dpp v163, v103, v143 row_shr:1 row_mask:0xf bank_mask:0xf
	v_fmac_f32_dpp v164, v88, v132 row_shr:1 row_mask:0xf bank_mask:0xf
	v_fmac_f32_dpp v165, v89, v133 row_shr:1 row_mask:0xf bank_mask:0xf
	v_fmac_f32_dpp v166, v90, v134 row_shr:1 row_mask:0xf bank_mask:0xf
	v_fmac_f32_dpp v167, v91, v135 row_shr:1 row_mask:0xf bank_mask:0xf
	v_fmac_f32_dpp v160, v116, v140 row_shl:15 row_mask:0xf bank_mask:0xf
	v_fmac_f32_dpp v161, v117, v141 row_shl:15 row_mask:0xf bank_mask:0xf
	v_fmac_f32_dpp v162, v118, v142 row_shl:15 row_mask:0xf bank_mask:0xf
	v_fmac_f32_dpp v163, v119, v143 row_shl:15 row_mask:0xf bank_mask:0xf
	v_fmac_f32_dpp v164, v104, v132 row_shl:15 row_mask:0xf bank_mask:0xf
	v_fmac_f32_dpp v165, v105, v133 row_shl:15 row_mask:0xf bank_mask:0xf
	v_fmac_f32_dpp v166, v106, v134 row_shl:15 row_mask:0xf bank_mask:0xf
	v_fmac_f32_dpp v167, v107, v135 row_shl:15 row_mask:0xf bank_mask:0xf
	v_fmac_f32_dpp v160, v100, v136 row_shr:2 row_mask:0xf bank_mask:0xf
	v_fmac_f32_dpp v161, v101, v137 row_shr:2 row_mask:0xf bank_mask:0xf
	v_fmac_f32_dpp v162, v102, v138 row_shr:2 row_mask:0xf bank_mask:0xf
	v_fmac_f32_dpp v163, v103, v139 row_shr:2 row_mask:0xf bank_mask:0xf
	v_fmac_f32_dpp v164, v88, v128 row_shr:2 row_mask:0xf bank_mask:0xf
	v_fmac_f32_dpp v165, v89, v129 row_shr:2 row_mask:0xf bank_mask:0xf
	v_fmac_f32_dpp v166, v90, v130 row_shr:2 row_mask:0xf bank_mask:0xf
	v_fmac_f32_dpp v167, v91, v131 row_shr:2 row_mask:0xf bank_mask:0xf
	v_fmac_f32_dpp v160, v116, v136 row_shl:14 row_mask:0xf bank_mask:0xf
	v_fmac_f32_dpp v161, v117, v137 row_shl:14 row_mask:0xf bank_mask:0xf
	v_fmac_f32_dpp v162, v118, v138 row_shl:14 row_mask:0xf bank_mask:0xf
	v_fmac_f32_dpp v163, v119, v139 row_shl:14 row_mask:0xf bank_mask:0xf
	v_fmac_f32_dpp v164, v104, v128 row_shl:14 row_mask:0xf bank_mask:0xf
	v_fmac_f32_dpp v165, v105, v129 row_shl:14 row_mask:0xf bank_mask:0xf
	v_fmac_f32_dpp v166, v106, v130 row_shl:14 row_mask:0xf bank_mask:0xf
	v_fmac_f32_dpp v167, v107, v131 row_shl:14 row_mask:0xf bank_mask:0xf
	v_mul_f32_e32 v168, 0xbfb8aa3b, v160
	v_mul_f32_e32 v169, 0xbfb8aa3b, v161
	v_mul_f32_e32 v170, 0xbfb8aa3b, v162
	v_mul_f32_e32 v171, 0xbfb8aa3b, v163
	v_exp_f32_e32 v168, v168
	v_exp_f32_e32 v169, v169
	v_exp_f32_e32 v170, v170
	v_exp_f32_e32 v171, v171
	v_add_f32_e32 v168, 1.0, v168
	v_add_f32_e32 v169, 1.0, v169
	v_add_f32_e32 v170, 1.0, v170
	v_add_f32_e32 v171, 1.0, v171
	v_rcp_f32_e32 v168, v168
	v_rcp_f32_e32 v169, v169
	v_rcp_f32_e32 v170, v170
	v_rcp_f32_e32 v171, v171
	s_mov_b32 s80, 0x2c000
	s_mov_b32 s81, 0
; DI float silu_fast(float x) { return x * __builtin_amdgcn_rcpf(1.f + __expf(-x)); }
; template <int CTRL> DI float dppf(float v) { return __builtin_bit_cast(float, __builtin_amdgcn_update_dpp(0, __builtin_bit_cast(int, v), CTRL, 0xf, 0xf, true)); }
; DI void Epi::fused(const f32x4 (&acc)[2][2][4][2], int pm, int pn, int wr, int wc, int fr, int fq) const {
;     ...
;         const int ncol = pn * 256 + bj * 128 + wc * 32 + 8 * fq, j0 = (ncol >> 3) * 4;
;         const f32x4 wa0 = *(const f32x4*)(E.cf0 + j0), wa1 = *(const f32x4*)(E.cf0 + FF2 + j0), wa2 = *(const f32x4*)(E.cf0 + 2 * FF2 + j0);
;         const f32x4 wb0 = *(const f32x4*)(E.cf0 + FFH + j0), wb1 = *(const f32x4*)(E.cf0 + FF2 + FFH + j0), wb2 = *(const f32x4*)(E.cf0 + 2 * FF2 + FFH + j0);
;         const f32x4 ba = *(const f32x4*)(E.cf1 + j0), bb = *(const f32x4*)(E.cf1 + FFH + j0);
;     ...
;             for (int m = 0; m < 4; ++m) {
;                 const f32x4 ca = acc[ai][bj][m][0], cb = acc[ai][bj][m][1];
;                 const int row = pm * 256 + ai * 128 + wr * 64 + m * 16 + fr;
;                 float o[4];
; #pragma unroll
;                 for (int e = 0; e < 4; ++e) {
;                     const float a1 = dppf<0x111>(ca[e]) + dppf<0x10F>(pa[e]), a2 = dppf<0x112>(ca[e]) + dppf<0x10E>(pa[e]);
;                     const float b1 = dppf<0x111>(cb[e]) + dppf<0x10F>(pb[e]), b2 = dppf<0x112>(cb[e]) + dppf<0x10E>(pb[e]);
;                     const float ya = fmaf(wa0[e], a2, fmaf(wa1[e], a1, fmaf(wa2[e], ca[e], ba[e])));
;                     const float yb = fmaf(wb0[e], b2, fmaf(wb1[e], b1, fmaf(wb2[e], cb[e], bb[e])));
;                     o[e] = silu_fast(ya) * yb; }
;                 if (m > 0 || fr >= 2) { u32x2 w; w.x = pk2(o[0], o[1]); w.y = pk2(o[2], o[3]); *(u32x2*)(E.d0 + (size_t)row * FFH + j0) = w; }
;                 if ((m == 0 && fr < 2) || (m == 3 && fr >= 14)) { float* hb = E.f0 + ((size_t)(row >> 6) * 4 + (m == 0 ? fr : fr - 12)) * FF2 + ncol; *(f32x4*)hb = ca; *(f32x4*)(hb + 4) = cb; }
	v_lshl_add_u64 v[174:175], v[224:225], 0, s[80:81]
	v_mul_f32_e32 v160, v160, v168
	v_mul_f32_e32 v161, v161, v169
	v_mul_f32_e32 v162, v162, v170
	v_mul_f32_e32 v163, v163, v171
	v_mul_f32_e32 v160, v164, v160
	v_mul_f32_e32 v161, v165, v161
	v_mul_f32_e32 v162, v166, v162
	v_mul_f32_e32 v163, v167, v163
	v_cvt_pk_bf16_f32 v172, v160, v161
	v_cvt_pk_bf16_f32 v173, v162, v163
	global_store_dwordx2 v[174:175], v[172:173], off
	v_fma_f32 v208, v152, v84, v156
	v_fma_f32 v209, v153, v85, v157
	v_fma_f32 v210, v154, v86, v158
	v_fma_f32 v211, v155, v87, v159
	v_fma_f32 v212, v144, v72, v148
	v_fma_f32 v213, v145, v73, v149
	v_fma_f32 v214, v146, v74, v150
	v_fma_f32 v215, v147, v75, v151
	v_fmac_f32_dpp v208, v84, v140 row_shr:1 row_mask:0xf bank_mask:0xf
	v_fmac_f32_dpp v209, v85, v141 row_shr:1 row_mask:0xf bank_mask:0xf
	v_fmac_f32_dpp v210, v86, v142 row_shr:1 row_mask:0xf bank_mask:0xf
	v_fmac_f32_dpp v211, v87, v143 row_shr:1 row_mask:0xf bank_mask:0xf
	v_fmac_f32_dpp v212, v72, v132 row_shr:1 row_mask:0xf bank_mask:0xf
	v_fmac_f32_dpp v213, v73, v133 row_shr:1 row_mask:0xf bank_mask:0xf
	v_fmac_f32_dpp v214, v74, v134 row_shr:1 row_mask:0xf bank_mask:0xf
	v_fmac_f32_dpp v215, v75, v135 row_shr:1 row_mask:0xf bank_mask:0xf
	v_fmac_f32_dpp v208, v100, v140 row_shl:15 row_mask:0xf bank_mask:0xf
	v_fmac_f32_dpp v209, v101, v141 row_shl:15 row_mask:0xf bank_mask:0xf
	v_fmac_f32_dpp v210, v102, v142 row_shl:15 row_mask:0xf bank_mask:0xf
	v_fmac_f32_dpp v211, v103, v143 row_shl:15 row_mask:0xf bank_mask:0xf
	v_fmac_f32_dpp v212, v88, v132 row_shl:15 row_mask:0xf bank_mask:0xf
	v_fmac_f32_dpp v213, v89, v133 row_shl:15 row_mask:0xf bank_mask:0xf
	v_fmac_f32_dpp v214, v90, v134 row_shl:15 row_mask:0xf bank_mask:0xf
	v_fmac_f32_dpp v215, v91, v135 row_shl:15 row_mask:0xf bank_mask:0xf
	v_fmac_f32_dpp v208, v84, v136 row_shr:2 row_mask:0xf bank_mask:0xf
	v_fmac_f32_dpp v209, v85, v137 row_shr:2 row_mask:0xf bank_mask:0xf
	v_fmac_f32_dpp v210, v86, v138 row_shr:2 row_mask:0xf bank_mask:0xf
	v_fmac_f32_dpp v211, v87, v139 row_shr:2 row_mask:0xf bank_mask:0xf
	v_fmac_f32_dpp v212, v72, v128 row_shr:2 row_mask:0xf bank_mask:0xf
	v_fmac_f32_dpp v213, v73, v129 row_shr:2 row_mask:0xf bank_mask:0xf
	v_fmac_f32_dpp v214, v74, v130 row_shr:2 row_mask:0xf bank_mask:0xf
	v_fmac_f32_dpp v215, v75, v131 row_shr:2 row_mask:0xf bank_mask:0xf
	v_fmac_f32_dpp v208, v100, v136 row_shl:14 row_mask:0xf bank_mask:0xf
	v_fmac_f32_dpp v209, v101, v137 row_shl:14 row_mask:0xf bank_mask:0xf
	v_fmac_f32_dpp v210, v102, v138 row_shl:14 row_mask:0xf bank_mask:0xf
	v_fmac_f32_dpp v211, v103, v139 row_shl:14 row_mask:0xf bank_mask:0xf
	v_fmac_f32_dpp v212, v88, v128 row_shl:14 row_mask:0xf bank_mask:0xf
	v_fmac_f32_dpp v213, v89, v129 row_shl:14 row_mask:0xf bank_mask:0xf
	v_fmac_f32_dpp v214, v90, v130 row_shl:14 row_mask:0xf bank_mask:0xf
	v_fmac_f32_dpp v215, v91, v131 row_shl:14 row_mask:0xf bank_mask:0xf
	v_mul_f32_e32 v216, 0xbfb8aa3b, v208
	v_mul_f32_e32 v217, 0xbfb8aa3b, v209
	v_mul_f32_e32 v218, 0xbfb8aa3b, v210
	v_mul_f32_e32 v219, 0xbfb8aa3b, v211
	v_exp_f32_e32 v216, v216
	v_exp_f32_e32 v217, v217
	v_exp_f32_e32 v218, v218
	v_exp_f32_e32 v219, v219
	v_add_f32_e32 v216, 1.0, v216
	v_add_f32_e32 v217, 1.0, v217
	v_add_f32_e32 v218, 1.0, v218
	v_add_f32_e32 v219, 1.0, v219
	v_rcp_f32_e32 v216, v216
	v_rcp_f32_e32 v217, v217
	v_rcp_f32_e32 v218, v218
	v_rcp_f32_e32 v219, v219
	s_mov_b32 s80, 0x42000
	s_mov_b32 s81, 0
	v_lshl_add_u64 v[222:223], v[224:225], 0, s[80:81]
	v_mul_f32_e32 v208, v208, v216
	v_mul_f32_e32 v209, v209, v217
	v_mul_f32_e32 v210, v210, v218
	v_mul_f32_e32 v211, v211, v219
	v_mul_f32_e32 v208, v212, v208
	v_mul_f32_e32 v209, v213, v209
	v_mul_f32_e32 v210, v214, v210
	v_mul_f32_e32 v211, v215, v211
	v_cvt_pk_bf16_f32 v220, v208, v209
	v_cvt_pk_bf16_f32 v221, v210, v211
	global_store_dwordx2 v[222:223], v[220:221], off
	s_ashr_i32 s80, s71, 6
	s_lshl_b32 s80, s80, 2
	v_add_u32_e32 v226, s80, v190
	v_mov_b64_e32 v[222:223], s[8:9]
	s_movk_i32 s80, 0x5800
	v_mad_i64_i32 v[222:223], s[78:79], v226, s80, v[222:223]
	v_lshl_add_u64 v[222:223], v[228:229], 2, v[222:223]
	s_and_saveexec_b64 s[76:77], s[42:43]
	global_store_dwordx4 v[222:223], v[84:87], off
	global_store_dwordx4 v[222:223], v[72:75], off offset:16
	s_or_b64 exec, exec, s[76:77]
	v_add_u32_e32 v238, 0x80, v240
	v_lshlrev_b32_e32 v238, 1, v238
	v_mov_b32_e32 v239, 0
	v_lshl_add_u64 v[84:85], s[22:23], 0, v[238:239]
	global_load_dwordx4 v[84:87], v[84:85], off
	v_readlane_b32 s76, v254, 54
	v_readlane_b32 s77, v254, 55
	s_nop 1
	v_lshl_add_u64 v[88:89], s[76:77], 0, v[238:239]
	global_load_dwordx4 v[88:91], v[88:89], off
	v_readlane_b32 s76, v254, 56
	v_readlane_b32 s77, v254, 57
	s_nop 1
	v_lshl_add_u64 v[100:101], s[76:77], 0, v[238:239]
	global_load_dwordx4 v[100:103], v[100:101], off
	v_readlane_b32 s76, v255, 4
	v_readlane_b32 s77, v255, 5
	s_nop 1
	v_lshl_add_u64 v[104:105], s[76:77], 0, v[238:239]
	global_load_dwordx4 v[104:107], v[104:105], off
	v_readlane_b32 s76, v255, 6
	v_readlane_b32 s77, v255, 7
	s_nop 1
	v_lshl_add_u64 v[116:117], s[76:77], 0, v[238:239]
	global_load_dwordx4 v[116:119], v[116:117], off
	v_readlane_b32 s76, v255, 8
	v_readlane_b32 s77, v255, 9
	s_nop 1
	v_lshl_add_u64 v[120:121], s[76:77], 0, v[238:239]
	global_load_dwordx4 v[120:123], v[120:121], off
	v_readlane_b32 s76, v254, 49
	v_readlane_b32 s77, v254, 50
	s_nop 1
	v_lshl_add_u64 v[124:125], s[76:77], 0, v[238:239]
	global_load_dwordx4 v[124:127], v[124:125], off
	v_lshl_add_u64 v[72:73], s[72:73], 0, v[238:239]
	global_load_dwordx4 v[72:75], v[72:73], off
	v_add_u32_e32 v228, 128, v199
; DI float silu_fast(float x) { return x * __builtin_amdgcn_rcpf(1.f + __expf(-x)); }
; template <int CTRL> DI float dppf(float v) { return __builtin_bit_cast(float, __builtin_amdgcn_update_dpp(0, __builtin_bit_cast(int, v), CTRL, 0xf, 0xf, true)); }
; DI void Epi::fused(const f32x4 (&acc)[2][2][4][2], int pm, int pn, int wr, int wc, int fr, int fq) const {
;     ...
;         for (int ai = 0; ai < 2; ++ai) {
;             f32x4 pa = (f32x4){0.f, 0.f, 0.f, 0.f}, pb = pa;
; #pragma unroll
;             for (int m = 0; m < 4; ++m) {
;                 const f32x4 ca = acc[ai][bj][m][0], cb = acc[ai][bj][m][1];
;                 const int row = pm * 256 + ai * 128 + wr * 64 + m * 16 + fr;
;                 float o[4];
; #pragma unroll
;                 for (int e = 0; e < 4; ++e) {
;                     const float a1 = dppf<0x111>(ca[e]) + dppf<0x10F>(pa[e]), a2 = dppf<0x112>(ca[e]) + dppf<0x10E>(pa[e]);
;                     const float b1 = dppf<0x111>(cb[e]) + dppf<0x10F>(pb[e]), b2 = dppf<0x112>(cb[e]) + dppf<0x10E>(pb[e]);
;                     const float ya = fmaf(wa0[e], a2, fmaf(wa1[e], a1, fmaf(wa2[e], ca[e], ba[e])));
;                     const float yb = fmaf(wb0[e], b2, fmaf(wb1[e], b1, fmaf(wb2[e], cb[e], bb[e])));
;                     o[e] = silu_fast(ya) * yb; }
;                 if (m > 0 || fr >= 2) { u32x2 w; w.x = pk2(o[0], o[1]); w.y = pk2(o[2], o[3]); *(u32x2*)(E.d0 + (size_t)row * FFH + j0) = w; }
;                 if ((m == 0 && fr < 2) || (m == 3 && fr >= 14)) { float* hb = E.f0 + ((size_t)(row >> 6) * 4 + (m == 0 ? fr : fr - 12)) * FF2 + ncol; *(f32x4*)hb = ca; *(f32x4*)(hb + 4) = cb; }
	v_mov_b64_e32 v[224:225], s[12:13]
	s_movk_i32 s80, 0x1600
	v_mad_i64_i32 v[224:225], s[78:79], v228, s80, v[224:225]
	v_mov_b32_e32 v228, v240
	v_mov_b32_e32 v229, 0
	v_lshl_add_u64 v[224:225], v[228:229], 0, v[224:225]
	v_fma_f32 v160, v152, v60, v156
	v_fma_f32 v161, v153, v61, v157
	v_fma_f32 v162, v154, v62, v158
	v_fma_f32 v163, v155, v63, v159
	v_fma_f32 v164, v144, v56, v148
	v_fma_f32 v165, v145, v57, v149
	v_fma_f32 v166, v146, v58, v150
	v_fma_f32 v167, v147, v59, v151
	v_fmac_f32_dpp v160, v60, v140 row_shr:1 row_mask:0xf bank_mask:0xf
	v_fmac_f32_dpp v161, v61, v141 row_shr:1 row_mask:0xf bank_mask:0xf
	v_fmac_f32_dpp v162, v62, v142 row_shr:1 row_mask:0xf bank_mask:0xf
	v_fmac_f32_dpp v163, v63, v143 row_shr:1 row_mask:0xf bank_mask:0xf
	v_fmac_f32_dpp v164, v56, v132 row_shr:1 row_mask:0xf bank_mask:0xf
	v_fmac_f32_dpp v165, v57, v133 row_shr:1 row_mask:0xf bank_mask:0xf
	v_fmac_f32_dpp v166, v58, v134 row_shr:1 row_mask:0xf bank_mask:0xf
	v_fmac_f32_dpp v167, v59, v135 row_shr:1 row_mask:0xf bank_mask:0xf
	v_fmac_f32_dpp v160, v60, v136 row_shr:2 row_mask:0xf bank_mask:0xf
	v_fmac_f32_dpp v161, v61, v137 row_shr:2 row_mask:0xf bank_mask:0xf
	v_fmac_f32_dpp v162, v62, v138 row_shr:2 row_mask:0xf bank_mask:0xf
	v_fmac_f32_dpp v163, v63, v139 row_shr:2 row_mask:0xf bank_mask:0xf
	v_fmac_f32_dpp v164, v56, v128 row_shr:2 row_mask:0xf bank_mask:0xf
	v_fmac_f32_dpp v165, v57, v129 row_shr:2 row_mask:0xf bank_mask:0xf
	v_fmac_f32_dpp v166, v58, v130 row_shr:2 row_mask:0xf bank_mask:0xf
	v_fmac_f32_dpp v167, v59, v131 row_shr:2 row_mask:0xf bank_mask:0xf
	v_mul_f32_e32 v168, 0xbfb8aa3b, v160
	v_mul_f32_e32 v169, 0xbfb8aa3b, v161
	v_mul_f32_e32 v170, 0xbfb8aa3b, v162
	v_mul_f32_e32 v171, 0xbfb8aa3b, v163
	v_exp_f32_e32 v168, v168
	v_exp_f32_e32 v169, v169
	v_exp_f32_e32 v170, v170
	v_exp_f32_e32 v171, v171
	v_add_f32_e32 v168, 1.0, v168
	v_add_f32_e32 v169, 1.0, v169
	v_add_f32_e32 v170, 1.0, v170
	v_add_f32_e32 v171, 1.0, v171
	v_rcp_f32_e32 v168, v168
	v_rcp_f32_e32 v169, v169
	v_rcp_f32_e32 v170, v170
	v_rcp_f32_e32 v171, v171
	v_mov_b64_e32 v[174:175], v[224:225]
	v_mul_f32_e32 v160, v160, v168
	v_mul_f32_e32 v161, v161, v169
	v_mul_f32_e32 v162, v162, v170
	v_mul_f32_e32 v163, v163, v171
	v_mul_f32_e32 v160, v164, v160
	v_mul_f32_e32 v161, v165, v161
	v_mul_f32_e32 v162, v166, v162
	v_mul_f32_e32 v163, v167, v163
	v_cvt_pk_bf16_f32 v172, v160, v161
	v_cvt_pk_bf16_f32 v173, v162, v163
	s_and_saveexec_b64 s[76:77], s[38:39]
	global_store_dwordx2 v[174:175], v[172:173], off
	s_or_b64 exec, exec, s[76:77]
	s_ashr_i32 s80, s71, 6
	s_lshl_b32 s80, s80, 2
	s_add_i32 s80, s80, 8
	v_add_u32_e32 v226, s80, v188
	v_mov_b64_e32 v[174:175], s[8:9]
	s_movk_i32 s80, 0x5800
	v_mad_i64_i32 v[174:175], s[78:79], v226, s80, v[174:175]
	v_lshl_add_u64 v[174:175], v[228:229], 2, v[174:175]
	s_and_saveexec_b64 s[76:77], s[40:41]
	global_store_dwordx4 v[174:175], v[60:63], off
	global_store_dwordx4 v[174:175], v[56:59], off offset:16
	s_or_b64 exec, exec, s[76:77]
	v_fma_f32 v208, v152, v52, v156
	v_fma_f32 v209, v153, v53, v157
	v_fma_f32 v210, v154, v54, v158
	v_fma_f32 v211, v155, v55, v159
	v_fma_f32 v212, v144, v40, v148
	v_fma_f32 v213, v145, v41, v149
	v_fma_f32 v214, v146, v42, v150
	v_fma_f32 v215, v147, v43, v151
	v_fmac_f32_dpp v208, v52, v140 row_shr:1 row_mask:0xf bank_mask:0xf
	v_fmac_f32_dpp v209, v53, v141 row_shr:1 row_mask:0xf bank_mask:0xf
	v_fmac_f32_dpp v210, v54, v142 row_shr:1 row_mask:0xf bank_mask:0xf
	v_fmac_f32_dpp v211, v55, v143 row_shr:1 row_mask:0xf bank_mask:0xf
	v_fmac_f32_dpp v212, v40, v132 row_shr:1 row_mask:0xf bank_mask:0xf
	v_fmac_f32_dpp v213, v41, v133 row_shr:1 row_mask:0xf bank_mask:0xf
	v_fmac_f32_dpp v214, v42, v134 row_shr:1 row_mask:0xf bank_mask:0xf
	v_fmac_f32_dpp v215, v43, v135 row_shr:1 row_mask:0xf bank_mask:0xf
	v_fmac_f32_dpp v208, v60, v140 row_shl:15 row_mask:0xf bank_mask:0xf
	v_fmac_f32_dpp v209, v61, v141 row_shl:15 row_mask:0xf bank_mask:0xf
	v_fmac_f32_dpp v210, v62, v142 row_shl:15 row_mask:0xf bank_mask:0xf
	v_fmac_f32_dpp v211, v63, v143 row_shl:15 row_mask:0xf bank_mask:0xf
	v_fmac_f32_dpp v212, v56, v132 row_shl:15 row_mask:0xf bank_mask:0xf
	v_fmac_f32_dpp v213, v57, v133 row_shl:15 row_mask:0xf bank_mask:0xf
	v_fmac_f32_dpp v214, v58, v134 row_shl:15 row_mask:0xf bank_mask:0xf
	v_fmac_f32_dpp v215, v59, v135 row_shl:15 row_mask:0xf bank_mask:0xf
	v_fmac_f32_dpp v208, v52, v136 row_shr:2 row_mask:0xf bank_mask:0xf
	v_fmac_f32_dpp v209, v53, v137 row_shr:2 row_mask:0xf bank_mask:0xf
	v_fmac_f32_dpp v210, v54, v138 row_shr:2 row_mask:0xf bank_mask:0xf
	v_fmac_f32_dpp v211, v55, v139 row_shr:2 row_mask:0xf bank_mask:0xf
	v_fmac_f32_dpp v212, v40, v128 row_shr:2 row_mask:0xf bank_mask:0xf
	v_fmac_f32_dpp v213, v41, v129 row_shr:2 row_mask:0xf bank_mask:0xf
	v_fmac_f32_dpp v214, v42, v130 row_shr:2 row_mask:0xf bank_mask:0xf
	v_fmac_f32_dpp v215, v43, v131 row_shr:2 row_mask:0xf bank_mask:0xf
	v_fmac_f32_dpp v208, v60, v136 row_shl:14 row_mask:0xf bank_mask:0xf
	v_fmac_f32_dpp v209, v61, v137 row_shl:14 row_mask:0xf bank_mask:0xf
	v_fmac_f32_dpp v210, v62, v138 row_shl:14 row_mask:0xf bank_mask:0xf
	v_fmac_f32_dpp v211, v63, v139 row_shl:14 row_mask:0xf bank_mask:0xf
	v_fmac_f32_dpp v212, v56, v128 row_shl:14 row_mask:0xf bank_mask:0xf
	v_fmac_f32_dpp v213, v57, v129 row_shl:14 row_mask:0xf bank_mask:0xf
	v_fmac_f32_dpp v214, v58, v130 row_shl:14 row_mask:0xf bank_mask:0xf
	v_fmac_f32_dpp v215, v59, v131 row_shl:14 row_mask:0xf bank_mask:0xf
	v_mul_f32_e32 v216, 0xbfb8aa3b, v208
	v_mul_f32_e32 v217, 0xbfb8aa3b, v209
	v_mul_f32_e32 v218, 0xbfb8aa3b, v210
	v_mul_f32_e32 v219, 0xbfb8aa3b, v211
; DI float silu_fast(float x) { return x * __builtin_amdgcn_rcpf(1.f + __expf(-x)); }
; template <int CTRL> DI float dppf(float v) { return __builtin_bit_cast(float, __builtin_amdgcn_update_dpp(0, __builtin_bit_cast(int, v), CTRL, 0xf, 0xf, true)); }
; DI void Epi::fused(const f32x4 (&acc)[2][2][4][2], int pm, int pn, int wr, int wc, int fr, int fq) const {
;     ...
;             for (int m = 0; m < 4; ++m) {
;                 const f32x4 ca = acc[ai][bj][m][0], cb = acc[ai][bj][m][1];
;                 const int row = pm * 256 + ai * 128 + wr * 64 + m * 16 + fr;
;                 float o[4];
; #pragma unroll
;                 for (int e = 0; e < 4; ++e) {
;                     const float a1 = dppf<0x111>(ca[e]) + dppf<0x10F>(pa[e]), a2 = dppf<0x112>(ca[e]) + dppf<0x10E>(pa[e]);
;                     const float b1 = dppf<0x111>(cb[e]) + dppf<0x10F>(pb[e]), b2 = dppf<0x112>(cb[e]) + dppf<0x10E>(pb[e]);
;                     const float ya = fmaf(wa0[e], a2, fmaf(wa1[e], a1, fmaf(wa2[e], ca[e], ba[e])));
;                     const float yb = fmaf(wb0[e], b2, fmaf(wb1[e], b1, fmaf(wb2[e], cb[e], bb[e])));
;                     o[e] = silu_fast(ya) * yb; }
;                 if (m > 0 || fr >= 2) { u32x2 w; w.x = pk2(o[0], o[1]); w.y = pk2(o[2], o[3]); *(u32x2*)(E.d0 + (size_t)row * FFH + j0) = w; }
	v_exp_f32_e32 v216, v216
	v_exp_f32_e32 v217, v217
	v_exp_f32_e32 v218, v218
	v_exp_f32_e32 v219, v219
	v_add_f32_e32 v216, 1.0, v216
	v_add_f32_e32 v217, 1.0, v217
	v_add_f32_e32 v218, 1.0, v218
	v_add_f32_e32 v219, 1.0, v219
	v_rcp_f32_e32 v216, v216
	v_rcp_f32_e32 v217, v217
	v_rcp_f32_e32 v218, v218
	v_rcp_f32_e32 v219, v219
	s_mov_b32 s80, 0x16000
	s_mov_b32 s81, 0
	v_lshl_add_u64 v[222:223], v[224:225], 0, s[80:81]
	v_mul_f32_e32 v208, v208, v216
	v_mul_f32_e32 v209, v209, v217
	v_mul_f32_e32 v210, v210, v218
	v_mul_f32_e32 v211, v211, v219
	v_mul_f32_e32 v208, v212, v208
	v_mul_f32_e32 v209, v213, v209
	v_mul_f32_e32 v210, v214, v210
	v_mul_f32_e32 v211, v215, v211
	v_cvt_pk_bf16_f32 v220, v208, v209
	v_cvt_pk_bf16_f32 v221, v210, v211
	global_store_dwordx2 v[222:223], v[220:221], off
	v_fma_f32 v160, v152, v36, v156
	v_fma_f32 v161, v153, v37, v157
	v_fma_f32 v162, v154, v38, v158
	v_fma_f32 v163, v155, v39, v159
	v_fma_f32 v164, v144, v16, v148
	v_fma_f32 v165, v145, v17, v149
	v_fma_f32 v166, v146, v18, v150
	v_fma_f32 v167, v147, v19, v151
	v_fmac_f32_dpp v160, v36, v140 row_shr:1 row_mask:0xf bank_mask:0xf
	v_fmac_f32_dpp v161, v37, v141 row_shr:1 row_mask:0xf bank_mask:0xf
	v_fmac_f32_dpp v162, v38, v142 row_shr:1 row_mask:0xf bank_mask:0xf
	v_fmac_f32_dpp v163, v39, v143 row_shr:1 row_mask:0xf bank_mask:0xf
	v_fmac_f32_dpp v164, v16, v132 row_shr:1 row_mask:0xf bank_mask:0xf
	v_fmac_f32_dpp v165, v17, v133 row_shr:1 row_mask:0xf bank_mask:0xf
	v_fmac_f32_dpp v166, v18, v134 row_shr:1 row_mask:0xf bank_mask:0xf
	v_fmac_f32_dpp v167, v19, v135 row_shr:1 row_mask:0xf bank_mask:0xf
	v_fmac_f32_dpp v160, v52, v140 row_shl:15 row_mask:0xf bank_mask:0xf
	v_fmac_f32_dpp v161, v53, v141 row_shl:15 row_mask:0xf bank_mask:0xf
	v_fmac_f32_dpp v162, v54, v142 row_shl:15 row_mask:0xf bank_mask:0xf
	v_fmac_f32_dpp v163, v55, v143 row_shl:15 row_mask:0xf bank_mask:0xf
	v_fmac_f32_dpp v164, v40, v132 row_shl:15 row_mask:0xf bank_mask:0xf
	v_fmac_f32_dpp v165, v41, v133 row_shl:15 row_mask:0xf bank_mask:0xf
	v_fmac_f32_dpp v166, v42, v134 row_shl:15 row_mask:0xf bank_mask:0xf
	v_fmac_f32_dpp v167, v43, v135 row_shl:15 row_mask:0xf bank_mask:0xf
	v_fmac_f32_dpp v160, v36, v136 row_shr:2 row_mask:0xf bank_mask:0xf
	v_fmac_f32_dpp v161, v37, v137 row_shr:2 row_mask:0xf bank_mask:0xf
	v_fmac_f32_dpp v162, v38, v138 row_shr:2 row_mask:0xf bank_mask:0xf
	v_fmac_f32_dpp v163, v39, v139 row_shr:2 row_mask:0xf bank_mask:0xf
	v_fmac_f32_dpp v164, v16, v128 row_shr:2 row_mask:0xf bank_mask:0xf
	v_fmac_f32_dpp v165, v17, v129 row_shr:2 row_mask:0xf bank_mask:0xf
	v_fmac_f32_dpp v166, v18, v130 row_shr:2 row_mask:0xf bank_mask:0xf
	v_fmac_f32_dpp v167, v19, v131 row_shr:2 row_mask:0xf bank_mask:0xf
	v_fmac_f32_dpp v160, v52, v136 row_shl:14 row_mask:0xf bank_mask:0xf
	v_fmac_f32_dpp v161, v53, v137 row_shl:14 row_mask:0xf bank_mask:0xf
	v_fmac_f32_dpp v162, v54, v138 row_shl:14 row_mask:0xf bank_mask:0xf
	v_fmac_f32_dpp v163, v55, v139 row_shl:14 row_mask:0xf bank_mask:0xf
	v_fmac_f32_dpp v164, v40, v128 row_shl:14 row_mask:0xf bank_mask:0xf
	v_fmac_f32_dpp v165, v41, v129 row_shl:14 row_mask:0xf bank_mask:0xf
	v_fmac_f32_dpp v166, v42, v130 row_shl:14 row_mask:0xf bank_mask:0xf
	v_fmac_f32_dpp v167, v43, v131 row_shl:14 row_mask:0xf bank_mask:0xf
	v_mul_f32_e32 v168, 0xbfb8aa3b, v160
	v_mul_f32_e32 v169, 0xbfb8aa3b, v161
	v_mul_f32_e32 v170, 0xbfb8aa3b, v162
	v_mul_f32_e32 v171, 0xbfb8aa3b, v163
	v_exp_f32_e32 v168, v168
	v_exp_f32_e32 v169, v169
	v_exp_f32_e32 v170, v170
	v_exp_f32_e32 v171, v171
	v_add_f32_e32 v168, 1.0, v168
	v_add_f32_e32 v169, 1.0, v169
	v_add_f32_e32 v170, 1.0, v170
	v_add_f32_e32 v171, 1.0, v171
	v_rcp_f32_e32 v168, v168
	v_rcp_f32_e32 v169, v169
	v_rcp_f32_e32 v170, v170
	v_rcp_f32_e32 v171, v171
	s_mov_b32 s80, 0x2c000
	s_mov_b32 s81, 0
	v_lshl_add_u64 v[174:175], v[224:225], 0, s[80:81]
	v_mul_f32_e32 v160, v160, v168
	v_mul_f32_e32 v161, v161, v169
	v_mul_f32_e32 v162, v162, v170
	v_mul_f32_e32 v163, v163, v171
	v_mul_f32_e32 v160, v164, v160
	v_mul_f32_e32 v161, v165, v161
	v_mul_f32_e32 v162, v166, v162
	v_mul_f32_e32 v163, v167, v163
	v_cvt_pk_bf16_f32 v172, v160, v161
	v_cvt_pk_bf16_f32 v173, v162, v163
	global_store_dwordx2 v[174:175], v[172:173], off
	v_fma_f32 v208, v152, v12, v156
	v_fma_f32 v209, v153, v13, v157
	v_fma_f32 v210, v154, v14, v158
	v_fma_f32 v211, v155, v15, v159
	v_fma_f32 v212, v144, v0, v148
	v_fma_f32 v213, v145, v1, v149
	v_fma_f32 v214, v146, v2, v150
	v_fma_f32 v215, v147, v3, v151
	v_fmac_f32_dpp v208, v12, v140 row_shr:1 row_mask:0xf bank_mask:0xf
	v_fmac_f32_dpp v209, v13, v141 row_shr:1 row_mask:0xf bank_mask:0xf
	v_fmac_f32_dpp v210, v14, v142 row_shr:1 row_mask:0xf bank_mask:0xf
	v_fmac_f32_dpp v211, v15, v143 row_shr:1 row_mask:0xf bank_mask:0xf
	v_fmac_f32_dpp v212, v0, v132 row_shr:1 row_mask:0xf bank_mask:0xf
	v_fmac_f32_dpp v213, v1, v133 row_shr:1 row_mask:0xf bank_mask:0xf
	v_fmac_f32_dpp v214, v2, v134 row_shr:1 row_mask:0xf bank_mask:0xf
	v_fmac_f32_dpp v215, v3, v135 row_shr:1 row_mask:0xf bank_mask:0xf
	v_fmac_f32_dpp v208, v36, v140 row_shl:15 row_mask:0xf bank_mask:0xf
	v_fmac_f32_dpp v209, v37, v141 row_shl:15 row_mask:0xf bank_mask:0xf
	v_fmac_f32_dpp v210, v38, v142 row_shl:15 row_mask:0xf bank_mask:0xf
	v_fmac_f32_dpp v211, v39, v143 row_shl:15 row_mask:0xf bank_mask:0xf
	v_fmac_f32_dpp v212, v16, v132 row_shl:15 row_mask:0xf bank_mask:0xf
	v_fmac_f32_dpp v213, v17, v133 row_shl:15 row_mask:0xf bank_mask:0xf
	v_fmac_f32_dpp v214, v18, v134 row_shl:15 row_mask:0xf bank_mask:0xf
	v_fmac_f32_dpp v215, v19, v135 row_shl:15 row_mask:0xf bank_mask:0xf
; DI float silu_fast(float x) { return x * __builtin_amdgcn_rcpf(1.f + __expf(-x)); }
; template <int CTRL> DI float dppf(float v) { return __builtin_bit_cast(float, __builtin_amdgcn_update_dpp(0, __builtin_bit_cast(int, v), CTRL, 0xf, 0xf, true)); }
; DI void Epi::fused(const f32x4 (&acc)[2][2][4][2], int pm, int pn, int wr, int wc, int fr, int fq) const {
;     ...
;     for (int bj = 0; bj < 2; ++bj) {
;         const int ncol = pn * 256 + bj * 128 + wc * 32 + 8 * fq, j0 = (ncol >> 3) * 4;
;         const f32x4 wa0 = *(const f32x4*)(E.cf0 + j0), wa1 = *(const f32x4*)(E.cf0 + FF2 + j0), wa2 = *(const f32x4*)(E.cf0 + 2 * FF2 + j0);
;         const f32x4 wb0 = *(const f32x4*)(E.cf0 + FFH + j0), wb1 = *(const f32x4*)(E.cf0 + FF2 + FFH + j0), wb2 = *(const f32x4*)(E.cf0 + 2 * FF2 + FFH + j0);
;         const f32x4 ba = *(const f32x4*)(E.cf1 + j0), bb = *(const f32x4*)(E.cf1 + FFH + j0);
; #pragma unroll
;         for (int ai = 0; ai < 2; ++ai) {
;             f32x4 pa = (f32x4){0.f, 0.f, 0.f, 0.f}, pb = pa;
; #pragma unroll
;             for (int m = 0; m < 4; ++m) {
;                 const f32x4 ca = acc[ai][bj][m][0], cb = acc[ai][bj][m][1];
;                 const int row = pm * 256 + ai * 128 + wr * 64 + m * 16 + fr;
;                 float o[4];
; #pragma unroll
;                 for (int e = 0; e < 4; ++e) {
;                     const float a1 = dppf<0x111>(ca[e]) + dppf<0x10F>(pa[e]), a2 = dppf<0x112>(ca[e]) + dppf<0x10E>(pa[e]);
;                     const float b1 = dppf<0x111>(cb[e]) + dppf<0x10F>(pb[e]), b2 = dppf<0x112>(cb[e]) + dppf<0x10E>(pb[e]);
;                     const float ya = fmaf(wa0[e], a2, fmaf(wa1[e], a1, fmaf(wa2[e], ca[e], ba[e])));
;                     const float yb = fmaf(wb0[e], b2, fmaf(wb1[e], b1, fmaf(wb2[e], cb[e], bb[e])));
;                     o[e] = silu_fast(ya) * yb; }
;                 if (m > 0 || fr >= 2) { u32x2 w; w.x = pk2(o[0], o[1]); w.y = pk2(o[2], o[3]); *(u32x2*)(E.d0 + (size_t)row * FFH + j0) = w; }
;                 if ((m == 0 && fr < 2) || (m == 3 && fr >= 14)) { float* hb = E.f0 + ((size_t)(row >> 6) * 4 + (m == 0 ? fr : fr - 12)) * FF2 + ncol; *(f32x4*)hb = ca; *(f32x4*)(hb + 4) = cb; }
	v_fmac_f32_dpp v208, v12, v136 row_shr:2 row_mask:0xf bank_mask:0xf
	v_fmac_f32_dpp v209, v13, v137 row_shr:2 row_mask:0xf bank_mask:0xf
	v_fmac_f32_dpp v210, v14, v138 row_shr:2 row_mask:0xf bank_mask:0xf
	v_fmac_f32_dpp v211, v15, v139 row_shr:2 row_mask:0xf bank_mask:0xf
	v_fmac_f32_dpp v212, v0, v128 row_shr:2 row_mask:0xf bank_mask:0xf
	v_fmac_f32_dpp v213, v1, v129 row_shr:2 row_mask:0xf bank_mask:0xf
	v_fmac_f32_dpp v214, v2, v130 row_shr:2 row_mask:0xf bank_mask:0xf
	v_fmac_f32_dpp v215, v3, v131 row_shr:2 row_mask:0xf bank_mask:0xf
	v_fmac_f32_dpp v208, v36, v136 row_shl:14 row_mask:0xf bank_mask:0xf
	v_fmac_f32_dpp v209, v37, v137 row_shl:14 row_mask:0xf bank_mask:0xf
	v_fmac_f32_dpp v210, v38, v138 row_shl:14 row_mask:0xf bank_mask:0xf
	v_fmac_f32_dpp v211, v39, v139 row_shl:14 row_mask:0xf bank_mask:0xf
	v_fmac_f32_dpp v212, v16, v128 row_shl:14 row_mask:0xf bank_mask:0xf
	v_fmac_f32_dpp v213, v17, v129 row_shl:14 row_mask:0xf bank_mask:0xf
	v_fmac_f32_dpp v214, v18, v130 row_shl:14 row_mask:0xf bank_mask:0xf
	v_fmac_f32_dpp v215, v19, v131 row_shl:14 row_mask:0xf bank_mask:0xf
	v_mul_f32_e32 v216, 0xbfb8aa3b, v208
	v_mul_f32_e32 v217, 0xbfb8aa3b, v209
	v_mul_f32_e32 v218, 0xbfb8aa3b, v210
	v_mul_f32_e32 v219, 0xbfb8aa3b, v211
	v_exp_f32_e32 v216, v216
	v_exp_f32_e32 v217, v217
	v_exp_f32_e32 v218, v218
	v_exp_f32_e32 v219, v219
	v_add_f32_e32 v216, 1.0, v216
	v_add_f32_e32 v217, 1.0, v217
	v_add_f32_e32 v218, 1.0, v218
	v_add_f32_e32 v219, 1.0, v219
	v_rcp_f32_e32 v216, v216
	v_rcp_f32_e32 v217, v217
	v_rcp_f32_e32 v218, v218
	v_rcp_f32_e32 v219, v219
	s_mov_b32 s80, 0x42000
	s_mov_b32 s81, 0
	v_lshl_add_u64 v[222:223], v[224:225], 0, s[80:81]
	v_mul_f32_e32 v208, v208, v216
	v_mul_f32_e32 v209, v209, v217
	v_mul_f32_e32 v210, v210, v218
	v_mul_f32_e32 v211, v211, v219
	v_mul_f32_e32 v208, v212, v208
	v_mul_f32_e32 v209, v213, v209
	v_mul_f32_e32 v210, v214, v210
	v_mul_f32_e32 v211, v215, v211
	v_cvt_pk_bf16_f32 v220, v208, v209
	v_cvt_pk_bf16_f32 v221, v210, v211
	global_store_dwordx2 v[222:223], v[220:221], off
	s_ashr_i32 s80, s71, 6
	s_lshl_b32 s80, s80, 2
	s_add_i32 s80, s80, 8
	v_add_u32_e32 v226, s80, v190
	v_mov_b64_e32 v[222:223], s[8:9]
	s_movk_i32 s80, 0x5800
	v_mad_i64_i32 v[222:223], s[78:79], v226, s80, v[222:223]
	v_lshl_add_u64 v[222:223], v[228:229], 2, v[222:223]
	s_and_saveexec_b64 s[76:77], s[42:43]
	global_store_dwordx4 v[222:223], v[12:15], off
	global_store_dwordx4 v[222:223], v[0:3], off offset:16
	s_or_b64 exec, exec, s[76:77]
	v_mov_b32_e32 v228, v199
	v_mov_b64_e32 v[224:225], s[12:13]
	s_movk_i32 s80, 0x1600
	v_mad_i64_i32 v[224:225], s[78:79], v228, s80, v[224:225]
	v_add_u32_e32 v228, 128, v240
	v_mov_b32_e32 v229, 0
	v_lshl_add_u64 v[224:225], v[228:229], 0, v[224:225]
	s_waitcnt vmcnt(8)
	v_fma_f32 v160, v100, v112, v124
	v_fma_f32 v161, v101, v113, v125
	v_fma_f32 v162, v102, v114, v126
	v_fma_f32 v163, v103, v115, v127
	v_fma_f32 v164, v120, v108, v72
	v_fma_f32 v165, v121, v109, v73
	v_fma_f32 v166, v122, v110, v74
	v_fma_f32 v167, v123, v111, v75
	v_fmac_f32_dpp v160, v112, v88 row_shr:1 row_mask:0xf bank_mask:0xf
	v_fmac_f32_dpp v161, v113, v89 row_shr:1 row_mask:0xf bank_mask:0xf
	v_fmac_f32_dpp v162, v114, v90 row_shr:1 row_mask:0xf bank_mask:0xf
	v_fmac_f32_dpp v163, v115, v91 row_shr:1 row_mask:0xf bank_mask:0xf
	v_fmac_f32_dpp v164, v108, v116 row_shr:1 row_mask:0xf bank_mask:0xf
	v_fmac_f32_dpp v165, v109, v117 row_shr:1 row_mask:0xf bank_mask:0xf
	v_fmac_f32_dpp v166, v110, v118 row_shr:1 row_mask:0xf bank_mask:0xf
	v_fmac_f32_dpp v167, v111, v119 row_shr:1 row_mask:0xf bank_mask:0xf
	v_fmac_f32_dpp v160, v112, v84 row_shr:2 row_mask:0xf bank_mask:0xf
	v_fmac_f32_dpp v161, v113, v85 row_shr:2 row_mask:0xf bank_mask:0xf
	v_fmac_f32_dpp v162, v114, v86 row_shr:2 row_mask:0xf bank_mask:0xf
	v_fmac_f32_dpp v163, v115, v87 row_shr:2 row_mask:0xf bank_mask:0xf
	v_fmac_f32_dpp v164, v108, v104 row_shr:2 row_mask:0xf bank_mask:0xf
	v_fmac_f32_dpp v165, v109, v105 row_shr:2 row_mask:0xf bank_mask:0xf
	v_fmac_f32_dpp v166, v110, v106 row_shr:2 row_mask:0xf bank_mask:0xf
	v_fmac_f32_dpp v167, v111, v107 row_shr:2 row_mask:0xf bank_mask:0xf
	v_mul_f32_e32 v168, 0xbfb8aa3b, v160
	v_mul_f32_e32 v169, 0xbfb8aa3b, v161
	v_mul_f32_e32 v170, 0xbfb8aa3b, v162
	v_mul_f32_e32 v171, 0xbfb8aa3b, v163
	v_exp_f32_e32 v168, v168
	v_exp_f32_e32 v169, v169
	v_exp_f32_e32 v170, v170
	v_exp_f32_e32 v171, v171
	v_add_f32_e32 v168, 1.0, v168
	v_add_f32_e32 v169, 1.0, v169
	v_add_f32_e32 v170, 1.0, v170
	v_add_f32_e32 v171, 1.0, v171
	v_rcp_f32_e32 v168, v168
	v_rcp_f32_e32 v169, v169
	v_rcp_f32_e32 v170, v170
	v_rcp_f32_e32 v171, v171
	v_mov_b64_e32 v[174:175], v[224:225]
	v_mul_f32_e32 v160, v160, v168
	v_mul_f32_e32 v161, v161, v169
	v_mul_f32_e32 v162, v162, v170
	v_mul_f32_e32 v163, v163, v171
	v_mul_f32_e32 v160, v164, v160
	v_mul_f32_e32 v161, v165, v161
	v_mul_f32_e32 v162, v166, v162
	v_mul_f32_e32 v163, v167, v163
	v_cvt_pk_bf16_f32 v172, v160, v161
	v_cvt_pk_bf16_f32 v173, v162, v163
	s_and_saveexec_b64 s[76:77], s[38:39]
	global_store_dwordx2 v[174:175], v[172:173], off
	s_or_b64 exec, exec, s[76:77]
	s_ashr_i32 s80, s71, 6
	s_lshl_b32 s80, s80, 2
	v_add_u32_e32 v226, s80, v188
	v_mov_b64_e32 v[174:175], s[8:9]
	s_movk_i32 s80, 0x5800
	v_mad_i64_i32 v[174:175], s[78:79], v226, s80, v[174:175]
	v_lshl_add_u64 v[174:175], v[228:229], 2, v[174:175]
	s_and_saveexec_b64 s[76:77], s[40:41]
	global_store_dwordx4 v[174:175], v[112:115], off
	global_store_dwordx4 v[174:175], v[108:111], off offset:16
	s_or_b64 exec, exec, s[76:77]
	v_fma_f32 v208, v100, v96, v124
	v_fma_f32 v209, v101, v97, v125
; DI float silu_fast(float x) { return x * __builtin_amdgcn_rcpf(1.f + __expf(-x)); }
; template <int CTRL> DI float dppf(float v) { return __builtin_bit_cast(float, __builtin_amdgcn_update_dpp(0, __builtin_bit_cast(int, v), CTRL, 0xf, 0xf, true)); }
; DI void Epi::fused(const f32x4 (&acc)[2][2][4][2], int pm, int pn, int wr, int wc, int fr, int fq) const {
;     ...
;             for (int m = 0; m < 4; ++m) {
;                 const f32x4 ca = acc[ai][bj][m][0], cb = acc[ai][bj][m][1];
;                 const int row = pm * 256 + ai * 128 + wr * 64 + m * 16 + fr;
;                 float o[4];
; #pragma unroll
;                 for (int e = 0; e < 4; ++e) {
;                     const float a1 = dppf<0x111>(ca[e]) + dppf<0x10F>(pa[e]), a2 = dppf<0x112>(ca[e]) + dppf<0x10E>(pa[e]);
;                     const float b1 = dppf<0x111>(cb[e]) + dppf<0x10F>(pb[e]), b2 = dppf<0x112>(cb[e]) + dppf<0x10E>(pb[e]);
;                     const float ya = fmaf(wa0[e], a2, fmaf(wa1[e], a1, fmaf(wa2[e], ca[e], ba[e])));
;                     const float yb = fmaf(wb0[e], b2, fmaf(wb1[e], b1, fmaf(wb2[e], cb[e], bb[e])));
;                     o[e] = silu_fast(ya) * yb; }
;                 if (m > 0 || fr >= 2) { u32x2 w; w.x = pk2(o[0], o[1]); w.y = pk2(o[2], o[3]); *(u32x2*)(E.d0 + (size_t)row * FFH + j0) = w; }
	v_fma_f32 v210, v102, v98, v126
	v_fma_f32 v211, v103, v99, v127
	v_fma_f32 v212, v120, v92, v72
	v_fma_f32 v213, v121, v93, v73
	v_fma_f32 v214, v122, v94, v74
	v_fma_f32 v215, v123, v95, v75
	v_fmac_f32_dpp v208, v96, v88 row_shr:1 row_mask:0xf bank_mask:0xf
	v_fmac_f32_dpp v209, v97, v89 row_shr:1 row_mask:0xf bank_mask:0xf
	v_fmac_f32_dpp v210, v98, v90 row_shr:1 row_mask:0xf bank_mask:0xf
	v_fmac_f32_dpp v211, v99, v91 row_shr:1 row_mask:0xf bank_mask:0xf
	v_fmac_f32_dpp v212, v92, v116 row_shr:1 row_mask:0xf bank_mask:0xf
	v_fmac_f32_dpp v213, v93, v117 row_shr:1 row_mask:0xf bank_mask:0xf
	v_fmac_f32_dpp v214, v94, v118 row_shr:1 row_mask:0xf bank_mask:0xf
	v_fmac_f32_dpp v215, v95, v119 row_shr:1 row_mask:0xf bank_mask:0xf
	v_fmac_f32_dpp v208, v112, v88 row_shl:15 row_mask:0xf bank_mask:0xf
	v_fmac_f32_dpp v209, v113, v89 row_shl:15 row_mask:0xf bank_mask:0xf
	v_fmac_f32_dpp v210, v114, v90 row_shl:15 row_mask:0xf bank_mask:0xf
	v_fmac_f32_dpp v211, v115, v91 row_shl:15 row_mask:0xf bank_mask:0xf
	v_fmac_f32_dpp v212, v108, v116 row_shl:15 row_mask:0xf bank_mask:0xf
	v_fmac_f32_dpp v213, v109, v117 row_shl:15 row_mask:0xf bank_mask:0xf
	v_fmac_f32_dpp v214, v110, v118 row_shl:15 row_mask:0xf bank_mask:0xf
	v_fmac_f32_dpp v215, v111, v119 row_shl:15 row_mask:0xf bank_mask:0xf
	v_fmac_f32_dpp v208, v96, v84 row_shr:2 row_mask:0xf bank_mask:0xf
	v_fmac_f32_dpp v209, v97, v85 row_shr:2 row_mask:0xf bank_mask:0xf
	v_fmac_f32_dpp v210, v98, v86 row_shr:2 row_mask:0xf bank_mask:0xf
	v_fmac_f32_dpp v211, v99, v87 row_shr:2 row_mask:0xf bank_mask:0xf
	v_fmac_f32_dpp v212, v92, v104 row_shr:2 row_mask:0xf bank_mask:0xf
	v_fmac_f32_dpp v213, v93, v105 row_shr:2 row_mask:0xf bank_mask:0xf
	v_fmac_f32_dpp v214, v94, v106 row_shr:2 row_mask:0xf bank_mask:0xf
	v_fmac_f32_dpp v215, v95, v107 row_shr:2 row_mask:0xf bank_mask:0xf
	v_fmac_f32_dpp v208, v112, v84 row_shl:14 row_mask:0xf bank_mask:0xf
	v_fmac_f32_dpp v209, v113, v85 row_shl:14 row_mask:0xf bank_mask:0xf
	v_fmac_f32_dpp v210, v114, v86 row_shl:14 row_mask:0xf bank_mask:0xf
	v_fmac_f32_dpp v211, v115, v87 row_shl:14 row_mask:0xf bank_mask:0xf
	v_fmac_f32_dpp v212, v108, v104 row_shl:14 row_mask:0xf bank_mask:0xf
	v_fmac_f32_dpp v213, v109, v105 row_shl:14 row_mask:0xf bank_mask:0xf
	v_fmac_f32_dpp v214, v110, v106 row_shl:14 row_mask:0xf bank_mask:0xf
	v_fmac_f32_dpp v215, v111, v107 row_shl:14 row_mask:0xf bank_mask:0xf
	v_mul_f32_e32 v216, 0xbfb8aa3b, v208
	v_mul_f32_e32 v217, 0xbfb8aa3b, v209
	v_mul_f32_e32 v218, 0xbfb8aa3b, v210
	v_mul_f32_e32 v219, 0xbfb8aa3b, v211
	v_exp_f32_e32 v216, v216
	v_exp_f32_e32 v217, v217
	v_exp_f32_e32 v218, v218
	v_exp_f32_e32 v219, v219
	v_add_f32_e32 v216, 1.0, v216
	v_add_f32_e32 v217, 1.0, v217
	v_add_f32_e32 v218, 1.0, v218
	v_add_f32_e32 v219, 1.0, v219
	v_rcp_f32_e32 v216, v216
	v_rcp_f32_e32 v217, v217
	v_rcp_f32_e32 v218, v218
	v_rcp_f32_e32 v219, v219
	s_mov_b32 s80, 0x16000
	s_mov_b32 s81, 0
	v_lshl_add_u64 v[222:223], v[224:225], 0, s[80:81]
	v_mul_f32_e32 v208, v208, v216
	v_mul_f32_e32 v209, v209, v217
	v_mul_f32_e32 v210, v210, v218
	v_mul_f32_e32 v211, v211, v219
	v_mul_f32_e32 v208, v212, v208
	v_mul_f32_e32 v209, v213, v209
	v_mul_f32_e32 v210, v214, v210
	v_mul_f32_e32 v211, v215, v211
	v_cvt_pk_bf16_f32 v220, v208, v209
	v_cvt_pk_bf16_f32 v221, v210, v211
	global_store_dwordx2 v[222:223], v[220:221], off
	v_fma_f32 v160, v100, v80, v124
	v_fma_f32 v161, v101, v81, v125
	v_fma_f32 v162, v102, v82, v126
	v_fma_f32 v163, v103, v83, v127
	v_fma_f32 v164, v120, v76, v72
	v_fma_f32 v165, v121, v77, v73
	v_fma_f32 v166, v122, v78, v74
	v_fma_f32 v167, v123, v79, v75
	v_fmac_f32_dpp v160, v80, v88 row_shr:1 row_mask:0xf bank_mask:0xf
	v_fmac_f32_dpp v161, v81, v89 row_shr:1 row_mask:0xf bank_mask:0xf
	v_fmac_f32_dpp v162, v82, v90 row_shr:1 row_mask:0xf bank_mask:0xf
	v_fmac_f32_dpp v163, v83, v91 row_shr:1 row_mask:0xf bank_mask:0xf
	v_fmac_f32_dpp v164, v76, v116 row_shr:1 row_mask:0xf bank_mask:0xf
	v_fmac_f32_dpp v165, v77, v117 row_shr:1 row_mask:0xf bank_mask:0xf
	v_fmac_f32_dpp v166, v78, v118 row_shr:1 row_mask:0xf bank_mask:0xf
	v_fmac_f32_dpp v167, v79, v119 row_shr:1 row_mask:0xf bank_mask:0xf
	v_fmac_f32_dpp v160, v96, v88 row_shl:15 row_mask:0xf bank_mask:0xf
	v_fmac_f32_dpp v161, v97, v89 row_shl:15 row_mask:0xf bank_mask:0xf
	v_fmac_f32_dpp v162, v98, v90 row_shl:15 row_mask:0xf bank_mask:0xf
	v_fmac_f32_dpp v163, v99, v91 row_shl:15 row_mask:0xf bank_mask:0xf
	v_fmac_f32_dpp v164, v92, v116 row_shl:15 row_mask:0xf bank_mask:0xf
	v_fmac_f32_dpp v165, v93, v117 row_shl:15 row_mask:0xf bank_mask:0xf
	v_fmac_f32_dpp v166, v94, v118 row_shl:15 row_mask:0xf bank_mask:0xf
	v_fmac_f32_dpp v167, v95, v119 row_shl:15 row_mask:0xf bank_mask:0xf
	v_fmac_f32_dpp v160, v80, v84 row_shr:2 row_mask:0xf bank_mask:0xf
	v_fmac_f32_dpp v161, v81, v85 row_shr:2 row_mask:0xf bank_mask:0xf
	v_fmac_f32_dpp v162, v82, v86 row_shr:2 row_mask:0xf bank_mask:0xf
	v_fmac_f32_dpp v163, v83, v87 row_shr:2 row_mask:0xf bank_mask:0xf
	v_fmac_f32_dpp v164, v76, v104 row_shr:2 row_mask:0xf bank_mask:0xf
	v_fmac_f32_dpp v165, v77, v105 row_shr:2 row_mask:0xf bank_mask:0xf
	v_fmac_f32_dpp v166, v78, v106 row_shr:2 row_mask:0xf bank_mask:0xf
	v_fmac_f32_dpp v167, v79, v107 row_shr:2 row_mask:0xf bank_mask:0xf
	v_fmac_f32_dpp v160, v96, v84 row_shl:14 row_mask:0xf bank_mask:0xf
	v_fmac_f32_dpp v161, v97, v85 row_shl:14 row_mask:0xf bank_mask:0xf
	v_fmac_f32_dpp v162, v98, v86 row_shl:14 row_mask:0xf bank_mask:0xf
	v_fmac_f32_dpp v163, v99, v87 row_shl:14 row_mask:0xf bank_mask:0xf
	v_fmac_f32_dpp v164, v92, v104 row_shl:14 row_mask:0xf bank_mask:0xf
; DI float silu_fast(float x) { return x * __builtin_amdgcn_rcpf(1.f + __expf(-x)); }
; template <int CTRL> DI float dppf(float v) { return __builtin_bit_cast(float, __builtin_amdgcn_update_dpp(0, __builtin_bit_cast(int, v), CTRL, 0xf, 0xf, true)); }
; DI void Epi::fused(const f32x4 (&acc)[2][2][4][2], int pm, int pn, int wr, int wc, int fr, int fq) const {
;     ...
;             for (int m = 0; m < 4; ++m) {
;                 const f32x4 ca = acc[ai][bj][m][0], cb = acc[ai][bj][m][1];
;                 const int row = pm * 256 + ai * 128 + wr * 64 + m * 16 + fr;
;                 float o[4];
; #pragma unroll
;                 for (int e = 0; e < 4; ++e) {
;                     const float a1 = dppf<0x111>(ca[e]) + dppf<0x10F>(pa[e]), a2 = dppf<0x112>(ca[e]) + dppf<0x10E>(pa[e]);
;                     const float b1 = dppf<0x111>(cb[e]) + dppf<0x10F>(pb[e]), b2 = dppf<0x112>(cb[e]) + dppf<0x10E>(pb[e]);
;                     const float ya = fmaf(wa0[e], a2, fmaf(wa1[e], a1, fmaf(wa2[e], ca[e], ba[e])));
;                     const float yb = fmaf(wb0[e], b2, fmaf(wb1[e], b1, fmaf(wb2[e], cb[e], bb[e])));
;                     o[e] = silu_fast(ya) * yb; }
;                 if (m > 0 || fr >= 2) { u32x2 w; w.x = pk2(o[0], o[1]); w.y = pk2(o[2], o[3]); *(u32x2*)(E.d0 + (size_t)row * FFH + j0) = w; }
;                 if ((m == 0 && fr < 2) || (m == 3 && fr >= 14)) { float* hb = E.f0 + ((size_t)(row >> 6) * 4 + (m == 0 ? fr : fr - 12)) * FF2 + ncol; *(f32x4*)hb = ca; *(f32x4*)(hb + 4) = cb; }
	v_fmac_f32_dpp v165, v93, v105 row_shl:14 row_mask:0xf bank_mask:0xf
	v_fmac_f32_dpp v166, v94, v106 row_shl:14 row_mask:0xf bank_mask:0xf
	v_fmac_f32_dpp v167, v95, v107 row_shl:14 row_mask:0xf bank_mask:0xf
	v_mul_f32_e32 v168, 0xbfb8aa3b, v160
	v_mul_f32_e32 v169, 0xbfb8aa3b, v161
	v_mul_f32_e32 v170, 0xbfb8aa3b, v162
	v_mul_f32_e32 v171, 0xbfb8aa3b, v163
	v_exp_f32_e32 v168, v168
	v_exp_f32_e32 v169, v169
	v_exp_f32_e32 v170, v170
	v_exp_f32_e32 v171, v171
	v_add_f32_e32 v168, 1.0, v168
	v_add_f32_e32 v169, 1.0, v169
	v_add_f32_e32 v170, 1.0, v170
	v_add_f32_e32 v171, 1.0, v171
	v_rcp_f32_e32 v168, v168
	v_rcp_f32_e32 v169, v169
	v_rcp_f32_e32 v170, v170
	v_rcp_f32_e32 v171, v171
	s_mov_b32 s80, 0x2c000
	s_mov_b32 s81, 0
	v_lshl_add_u64 v[174:175], v[224:225], 0, s[80:81]
	v_mul_f32_e32 v160, v160, v168
	v_mul_f32_e32 v161, v161, v169
	v_mul_f32_e32 v162, v162, v170
	v_mul_f32_e32 v163, v163, v171
	v_mul_f32_e32 v160, v164, v160
	v_mul_f32_e32 v161, v165, v161
	v_mul_f32_e32 v162, v166, v162
	v_mul_f32_e32 v163, v167, v163
	v_cvt_pk_bf16_f32 v172, v160, v161
	v_cvt_pk_bf16_f32 v173, v162, v163
	global_store_dwordx2 v[174:175], v[172:173], off
	v_fma_f32 v208, v100, v68, v124
	v_fma_f32 v209, v101, v69, v125
	v_fma_f32 v210, v102, v70, v126
	v_fma_f32 v211, v103, v71, v127
	v_fma_f32 v212, v120, v64, v72
	v_fma_f32 v213, v121, v65, v73
	v_fma_f32 v214, v122, v66, v74
	v_fma_f32 v215, v123, v67, v75
	v_fmac_f32_dpp v208, v68, v88 row_shr:1 row_mask:0xf bank_mask:0xf
	v_fmac_f32_dpp v209, v69, v89 row_shr:1 row_mask:0xf bank_mask:0xf
	v_fmac_f32_dpp v210, v70, v90 row_shr:1 row_mask:0xf bank_mask:0xf
	v_fmac_f32_dpp v211, v71, v91 row_shr:1 row_mask:0xf bank_mask:0xf
	v_fmac_f32_dpp v212, v64, v116 row_shr:1 row_mask:0xf bank_mask:0xf
	v_fmac_f32_dpp v213, v65, v117 row_shr:1 row_mask:0xf bank_mask:0xf
	v_fmac_f32_dpp v214, v66, v118 row_shr:1 row_mask:0xf bank_mask:0xf
	v_fmac_f32_dpp v215, v67, v119 row_shr:1 row_mask:0xf bank_mask:0xf
	v_fmac_f32_dpp v208, v80, v88 row_shl:15 row_mask:0xf bank_mask:0xf
	v_fmac_f32_dpp v209, v81, v89 row_shl:15 row_mask:0xf bank_mask:0xf
	v_fmac_f32_dpp v210, v82, v90 row_shl:15 row_mask:0xf bank_mask:0xf
	v_fmac_f32_dpp v211, v83, v91 row_shl:15 row_mask:0xf bank_mask:0xf
	v_fmac_f32_dpp v212, v76, v116 row_shl:15 row_mask:0xf bank_mask:0xf
	v_fmac_f32_dpp v213, v77, v117 row_shl:15 row_mask:0xf bank_mask:0xf
	v_fmac_f32_dpp v214, v78, v118 row_shl:15 row_mask:0xf bank_mask:0xf
	v_fmac_f32_dpp v215, v79, v119 row_shl:15 row_mask:0xf bank_mask:0xf
	v_fmac_f32_dpp v208, v68, v84 row_shr:2 row_mask:0xf bank_mask:0xf
	v_fmac_f32_dpp v209, v69, v85 row_shr:2 row_mask:0xf bank_mask:0xf
	v_fmac_f32_dpp v210, v70, v86 row_shr:2 row_mask:0xf bank_mask:0xf
	v_fmac_f32_dpp v211, v71, v87 row_shr:2 row_mask:0xf bank_mask:0xf
	v_fmac_f32_dpp v212, v64, v104 row_shr:2 row_mask:0xf bank_mask:0xf
	v_fmac_f32_dpp v213, v65, v105 row_shr:2 row_mask:0xf bank_mask:0xf
	v_fmac_f32_dpp v214, v66, v106 row_shr:2 row_mask:0xf bank_mask:0xf
	v_fmac_f32_dpp v215, v67, v107 row_shr:2 row_mask:0xf bank_mask:0xf
	v_fmac_f32_dpp v208, v80, v84 row_shl:14 row_mask:0xf bank_mask:0xf
	v_fmac_f32_dpp v209, v81, v85 row_shl:14 row_mask:0xf bank_mask:0xf
	v_fmac_f32_dpp v210, v82, v86 row_shl:14 row_mask:0xf bank_mask:0xf
	v_fmac_f32_dpp v211, v83, v87 row_shl:14 row_mask:0xf bank_mask:0xf
	v_fmac_f32_dpp v212, v76, v104 row_shl:14 row_mask:0xf bank_mask:0xf
	v_fmac_f32_dpp v213, v77, v105 row_shl:14 row_mask:0xf bank_mask:0xf
	v_fmac_f32_dpp v214, v78, v106 row_shl:14 row_mask:0xf bank_mask:0xf
	v_fmac_f32_dpp v215, v79, v107 row_shl:14 row_mask:0xf bank_mask:0xf
	v_mul_f32_e32 v216, 0xbfb8aa3b, v208
	v_mul_f32_e32 v217, 0xbfb8aa3b, v209
	v_mul_f32_e32 v218, 0xbfb8aa3b, v210
	v_mul_f32_e32 v219, 0xbfb8aa3b, v211
	v_exp_f32_e32 v216, v216
	v_exp_f32_e32 v217, v217
	v_exp_f32_e32 v218, v218
	v_exp_f32_e32 v219, v219
	v_add_f32_e32 v216, 1.0, v216
	v_add_f32_e32 v217, 1.0, v217
	v_add_f32_e32 v218, 1.0, v218
	v_add_f32_e32 v219, 1.0, v219
	v_rcp_f32_e32 v216, v216
	v_rcp_f32_e32 v217, v217
	v_rcp_f32_e32 v218, v218
	v_rcp_f32_e32 v219, v219
	s_mov_b32 s80, 0x42000
	s_mov_b32 s81, 0
	v_lshl_add_u64 v[222:223], v[224:225], 0, s[80:81]
	v_mul_f32_e32 v208, v208, v216
	v_mul_f32_e32 v209, v209, v217
	v_mul_f32_e32 v210, v210, v218
	v_mul_f32_e32 v211, v211, v219
	v_mul_f32_e32 v208, v212, v208
	v_mul_f32_e32 v209, v213, v209
	v_mul_f32_e32 v210, v214, v210
	v_mul_f32_e32 v211, v215, v211
	v_cvt_pk_bf16_f32 v220, v208, v209
	v_cvt_pk_bf16_f32 v221, v210, v211
	global_store_dwordx2 v[222:223], v[220:221], off
	s_ashr_i32 s80, s71, 6
	s_lshl_b32 s80, s80, 2
	v_add_u32_e32 v226, s80, v190
	v_mov_b64_e32 v[222:223], s[8:9]
	s_movk_i32 s80, 0x5800
	v_mad_i64_i32 v[222:223], s[78:79], v226, s80, v[222:223]
	v_lshl_add_u64 v[222:223], v[228:229], 2, v[222:223]
	s_and_saveexec_b64 s[76:77], s[42:43]
	global_store_dwordx4 v[222:223], v[68:71], off
	global_store_dwordx4 v[222:223], v[64:67], off offset:16
	s_or_b64 exec, exec, s[76:77]
	v_add_u32_e32 v228, 128, v199
	v_mov_b64_e32 v[224:225], s[12:13]
	s_movk_i32 s80, 0x1600
	v_mad_i64_i32 v[224:225], s[78:79], v228, s80, v[224:225]
	v_add_u32_e32 v228, 128, v240
	v_mov_b32_e32 v229, 0
	v_lshl_add_u64 v[224:225], v[228:229], 0, v[224:225]
	v_fma_f32 v160, v100, v48, v124
	v_fma_f32 v161, v101, v49, v125
	v_fma_f32 v162, v102, v50, v126
	v_fma_f32 v163, v103, v51, v127
	v_fma_f32 v164, v120, v44, v72
	v_fma_f32 v165, v121, v45, v73
	v_fma_f32 v166, v122, v46, v74
	v_fma_f32 v167, v123, v47, v75
	v_fmac_f32_dpp v160, v48, v88 row_shr:1 row_mask:0xf bank_mask:0xf
	v_fmac_f32_dpp v161, v49, v89 row_shr:1 row_mask:0xf bank_mask:0xf
; DI float silu_fast(float x) { return x * __builtin_amdgcn_rcpf(1.f + __expf(-x)); }
; template <int CTRL> DI float dppf(float v) { return __builtin_bit_cast(float, __builtin_amdgcn_update_dpp(0, __builtin_bit_cast(int, v), CTRL, 0xf, 0xf, true)); }
; DI void Epi::fused(const f32x4 (&acc)[2][2][4][2], int pm, int pn, int wr, int wc, int fr, int fq) const {
;     ...
;         for (int ai = 0; ai < 2; ++ai) {
;             f32x4 pa = (f32x4){0.f, 0.f, 0.f, 0.f}, pb = pa;
; #pragma unroll
;             for (int m = 0; m < 4; ++m) {
;                 const f32x4 ca = acc[ai][bj][m][0], cb = acc[ai][bj][m][1];
;                 const int row = pm * 256 + ai * 128 + wr * 64 + m * 16 + fr;
;                 float o[4];
; #pragma unroll
;                 for (int e = 0; e < 4; ++e) {
;                     const float a1 = dppf<0x111>(ca[e]) + dppf<0x10F>(pa[e]), a2 = dppf<0x112>(ca[e]) + dppf<0x10E>(pa[e]);
;                     const float b1 = dppf<0x111>(cb[e]) + dppf<0x10F>(pb[e]), b2 = dppf<0x112>(cb[e]) + dppf<0x10E>(pb[e]);
;                     const float ya = fmaf(wa0[e], a2, fmaf(wa1[e], a1, fmaf(wa2[e], ca[e], ba[e])));
;                     const float yb = fmaf(wb0[e], b2, fmaf(wb1[e], b1, fmaf(wb2[e], cb[e], bb[e])));
;                     o[e] = silu_fast(ya) * yb; }
;                 if (m > 0 || fr >= 2) { u32x2 w; w.x = pk2(o[0], o[1]); w.y = pk2(o[2], o[3]); *(u32x2*)(E.d0 + (size_t)row * FFH + j0) = w; }
;                 if ((m == 0 && fr < 2) || (m == 3 && fr >= 14)) { float* hb = E.f0 + ((size_t)(row >> 6) * 4 + (m == 0 ? fr : fr - 12)) * FF2 + ncol; *(f32x4*)hb = ca; *(f32x4*)(hb + 4) = cb; }
	v_fmac_f32_dpp v162, v50, v90 row_shr:1 row_mask:0xf bank_mask:0xf
	v_fmac_f32_dpp v163, v51, v91 row_shr:1 row_mask:0xf bank_mask:0xf
	v_fmac_f32_dpp v164, v44, v116 row_shr:1 row_mask:0xf bank_mask:0xf
	v_fmac_f32_dpp v165, v45, v117 row_shr:1 row_mask:0xf bank_mask:0xf
	v_fmac_f32_dpp v166, v46, v118 row_shr:1 row_mask:0xf bank_mask:0xf
	v_fmac_f32_dpp v167, v47, v119 row_shr:1 row_mask:0xf bank_mask:0xf
	v_fmac_f32_dpp v160, v48, v84 row_shr:2 row_mask:0xf bank_mask:0xf
	v_fmac_f32_dpp v161, v49, v85 row_shr:2 row_mask:0xf bank_mask:0xf
	v_fmac_f32_dpp v162, v50, v86 row_shr:2 row_mask:0xf bank_mask:0xf
	v_fmac_f32_dpp v163, v51, v87 row_shr:2 row_mask:0xf bank_mask:0xf
	v_fmac_f32_dpp v164, v44, v104 row_shr:2 row_mask:0xf bank_mask:0xf
	v_fmac_f32_dpp v165, v45, v105 row_shr:2 row_mask:0xf bank_mask:0xf
	v_fmac_f32_dpp v166, v46, v106 row_shr:2 row_mask:0xf bank_mask:0xf
	v_fmac_f32_dpp v167, v47, v107 row_shr:2 row_mask:0xf bank_mask:0xf
	v_mul_f32_e32 v168, 0xbfb8aa3b, v160
	v_mul_f32_e32 v169, 0xbfb8aa3b, v161
	v_mul_f32_e32 v170, 0xbfb8aa3b, v162
	v_mul_f32_e32 v171, 0xbfb8aa3b, v163
	v_exp_f32_e32 v168, v168
	v_exp_f32_e32 v169, v169
	v_exp_f32_e32 v170, v170
	v_exp_f32_e32 v171, v171
	v_add_f32_e32 v168, 1.0, v168
	v_add_f32_e32 v169, 1.0, v169
	v_add_f32_e32 v170, 1.0, v170
	v_add_f32_e32 v171, 1.0, v171
	v_rcp_f32_e32 v168, v168
	v_rcp_f32_e32 v169, v169
	v_rcp_f32_e32 v170, v170
	v_rcp_f32_e32 v171, v171
	v_mov_b64_e32 v[174:175], v[224:225]
	v_mul_f32_e32 v160, v160, v168
	v_mul_f32_e32 v161, v161, v169
	v_mul_f32_e32 v162, v162, v170
	v_mul_f32_e32 v163, v163, v171
	v_mul_f32_e32 v160, v164, v160
	v_mul_f32_e32 v161, v165, v161
	v_mul_f32_e32 v162, v166, v162
	v_mul_f32_e32 v163, v167, v163
	v_cvt_pk_bf16_f32 v172, v160, v161
	v_cvt_pk_bf16_f32 v173, v162, v163
	s_and_saveexec_b64 s[76:77], s[38:39]
	global_store_dwordx2 v[174:175], v[172:173], off
	s_or_b64 exec, exec, s[76:77]
	s_ashr_i32 s80, s71, 6
	s_lshl_b32 s80, s80, 2
	s_add_i32 s80, s80, 8
	v_add_u32_e32 v226, s80, v188
	v_mov_b64_e32 v[174:175], s[8:9]
	s_movk_i32 s80, 0x5800
	v_mad_i64_i32 v[174:175], s[78:79], v226, s80, v[174:175]
	v_lshl_add_u64 v[174:175], v[228:229], 2, v[174:175]
	s_and_saveexec_b64 s[76:77], s[40:41]
	global_store_dwordx4 v[174:175], v[48:51], off
	global_store_dwordx4 v[174:175], v[44:47], off offset:16
	s_or_b64 exec, exec, s[76:77]
	v_fma_f32 v208, v100, v24, v124
	v_fma_f32 v209, v101, v25, v125
	v_fma_f32 v210, v102, v26, v126
	v_fma_f32 v211, v103, v27, v127
	v_fma_f32 v212, v120, v20, v72
	v_fma_f32 v213, v121, v21, v73
	v_fma_f32 v214, v122, v22, v74
	v_fma_f32 v215, v123, v23, v75
	v_fmac_f32_dpp v208, v24, v88 row_shr:1 row_mask:0xf bank_mask:0xf
	v_fmac_f32_dpp v209, v25, v89 row_shr:1 row_mask:0xf bank_mask:0xf
	v_fmac_f32_dpp v210, v26, v90 row_shr:1 row_mask:0xf bank_mask:0xf
	v_fmac_f32_dpp v211, v27, v91 row_shr:1 row_mask:0xf bank_mask:0xf
	v_fmac_f32_dpp v212, v20, v116 row_shr:1 row_mask:0xf bank_mask:0xf
	v_fmac_f32_dpp v213, v21, v117 row_shr:1 row_mask:0xf bank_mask:0xf
	v_fmac_f32_dpp v214, v22, v118 row_shr:1 row_mask:0xf bank_mask:0xf
	v_fmac_f32_dpp v215, v23, v119 row_shr:1 row_mask:0xf bank_mask:0xf
	v_fmac_f32_dpp v208, v48, v88 row_shl:15 row_mask:0xf bank_mask:0xf
	v_fmac_f32_dpp v209, v49, v89 row_shl:15 row_mask:0xf bank_mask:0xf
	v_fmac_f32_dpp v210, v50, v90 row_shl:15 row_mask:0xf bank_mask:0xf
	v_fmac_f32_dpp v211, v51, v91 row_shl:15 row_mask:0xf bank_mask:0xf
	v_fmac_f32_dpp v212, v44, v116 row_shl:15 row_mask:0xf bank_mask:0xf
	v_fmac_f32_dpp v213, v45, v117 row_shl:15 row_mask:0xf bank_mask:0xf
	v_fmac_f32_dpp v214, v46, v118 row_shl:15 row_mask:0xf bank_mask:0xf
	v_fmac_f32_dpp v215, v47, v119 row_shl:15 row_mask:0xf bank_mask:0xf
	v_fmac_f32_dpp v208, v24, v84 row_shr:2 row_mask:0xf bank_mask:0xf
	v_fmac_f32_dpp v209, v25, v85 row_shr:2 row_mask:0xf bank_mask:0xf
	v_fmac_f32_dpp v210, v26, v86 row_shr:2 row_mask:0xf bank_mask:0xf
	v_fmac_f32_dpp v211, v27, v87 row_shr:2 row_mask:0xf bank_mask:0xf
	v_fmac_f32_dpp v212, v20, v104 row_shr:2 row_mask:0xf bank_mask:0xf
	v_fmac_f32_dpp v213, v21, v105 row_shr:2 row_mask:0xf bank_mask:0xf
	v_fmac_f32_dpp v214, v22, v106 row_shr:2 row_mask:0xf bank_mask:0xf
	v_fmac_f32_dpp v215, v23, v107 row_shr:2 row_mask:0xf bank_mask:0xf
	v_fmac_f32_dpp v208, v48, v84 row_shl:14 row_mask:0xf bank_mask:0xf
	v_fmac_f32_dpp v209, v49, v85 row_shl:14 row_mask:0xf bank_mask:0xf
	v_fmac_f32_dpp v210, v50, v86 row_shl:14 row_mask:0xf bank_mask:0xf
	v_fmac_f32_dpp v211, v51, v87 row_shl:14 row_mask:0xf bank_mask:0xf
	v_fmac_f32_dpp v212, v44, v104 row_shl:14 row_mask:0xf bank_mask:0xf
	v_fmac_f32_dpp v213, v45, v105 row_shl:14 row_mask:0xf bank_mask:0xf
	v_fmac_f32_dpp v214, v46, v106 row_shl:14 row_mask:0xf bank_mask:0xf
	v_fmac_f32_dpp v215, v47, v107 row_shl:14 row_mask:0xf bank_mask:0xf
	v_mul_f32_e32 v216, 0xbfb8aa3b, v208
	v_mul_f32_e32 v217, 0xbfb8aa3b, v209
	v_mul_f32_e32 v218, 0xbfb8aa3b, v210
	v_mul_f32_e32 v219, 0xbfb8aa3b, v211
	v_exp_f32_e32 v216, v216
	v_exp_f32_e32 v217, v217
	v_exp_f32_e32 v218, v218
	v_exp_f32_e32 v219, v219
	v_add_f32_e32 v216, 1.0, v216
	v_add_f32_e32 v217, 1.0, v217
	v_add_f32_e32 v218, 1.0, v218
	v_add_f32_e32 v219, 1.0, v219
	v_rcp_f32_e32 v216, v216
	v_rcp_f32_e32 v217, v217
	v_rcp_f32_e32 v218, v218
	v_rcp_f32_e32 v219, v219
	s_mov_b32 s80, 0x16000
	s_mov_b32 s81, 0
	v_lshl_add_u64 v[222:223], v[224:225], 0, s[80:81]
	v_mul_f32_e32 v208, v208, v216
	v_mul_f32_e32 v209, v209, v217
	v_mul_f32_e32 v210, v210, v218
	v_mul_f32_e32 v211, v211, v219
	v_mul_f32_e32 v208, v212, v208
	v_mul_f32_e32 v209, v213, v209
	v_mul_f32_e32 v210, v214, v210
; DI float silu_fast(float x) { return x * __builtin_amdgcn_rcpf(1.f + __expf(-x)); }
; template <int CTRL> DI float dppf(float v) { return __builtin_bit_cast(float, __builtin_amdgcn_update_dpp(0, __builtin_bit_cast(int, v), CTRL, 0xf, 0xf, true)); }
; DI void Epi::fused(const f32x4 (&acc)[2][2][4][2], int pm, int pn, int wr, int wc, int fr, int fq) const {
;     ...
;             for (int m = 0; m < 4; ++m) {
;                 const f32x4 ca = acc[ai][bj][m][0], cb = acc[ai][bj][m][1];
;                 const int row = pm * 256 + ai * 128 + wr * 64 + m * 16 + fr;
;                 float o[4];
; #pragma unroll
;                 for (int e = 0; e < 4; ++e) {
;                     const float a1 = dppf<0x111>(ca[e]) + dppf<0x10F>(pa[e]), a2 = dppf<0x112>(ca[e]) + dppf<0x10E>(pa[e]);
;                     const float b1 = dppf<0x111>(cb[e]) + dppf<0x10F>(pb[e]), b2 = dppf<0x112>(cb[e]) + dppf<0x10E>(pb[e]);
;                     const float ya = fmaf(wa0[e], a2, fmaf(wa1[e], a1, fmaf(wa2[e], ca[e], ba[e])));
;                     const float yb = fmaf(wb0[e], b2, fmaf(wb1[e], b1, fmaf(wb2[e], cb[e], bb[e])));
;                     o[e] = silu_fast(ya) * yb; }
;                 if (m > 0 || fr >= 2) { u32x2 w; w.x = pk2(o[0], o[1]); w.y = pk2(o[2], o[3]); *(u32x2*)(E.d0 + (size_t)row * FFH + j0) = w; }
	v_mul_f32_e32 v211, v215, v211
	v_cvt_pk_bf16_f32 v220, v208, v209
	v_cvt_pk_bf16_f32 v221, v210, v211
	global_store_dwordx2 v[222:223], v[220:221], off
	v_fma_f32 v160, v100, v28, v124
	v_fma_f32 v161, v101, v29, v125
	v_fma_f32 v162, v102, v30, v126
	v_fma_f32 v163, v103, v31, v127
	v_fma_f32 v164, v120, v32, v72
	v_fma_f32 v165, v121, v33, v73
	v_fma_f32 v166, v122, v34, v74
	v_fma_f32 v167, v123, v35, v75
	v_fmac_f32_dpp v160, v28, v88 row_shr:1 row_mask:0xf bank_mask:0xf
	v_fmac_f32_dpp v161, v29, v89 row_shr:1 row_mask:0xf bank_mask:0xf
	v_fmac_f32_dpp v162, v30, v90 row_shr:1 row_mask:0xf bank_mask:0xf
	v_fmac_f32_dpp v163, v31, v91 row_shr:1 row_mask:0xf bank_mask:0xf
	v_fmac_f32_dpp v164, v32, v116 row_shr:1 row_mask:0xf bank_mask:0xf
	v_fmac_f32_dpp v165, v33, v117 row_shr:1 row_mask:0xf bank_mask:0xf
	v_fmac_f32_dpp v166, v34, v118 row_shr:1 row_mask:0xf bank_mask:0xf
	v_fmac_f32_dpp v167, v35, v119 row_shr:1 row_mask:0xf bank_mask:0xf
	v_fmac_f32_dpp v160, v24, v88 row_shl:15 row_mask:0xf bank_mask:0xf
	v_fmac_f32_dpp v161, v25, v89 row_shl:15 row_mask:0xf bank_mask:0xf
	v_fmac_f32_dpp v162, v26, v90 row_shl:15 row_mask:0xf bank_mask:0xf
	v_fmac_f32_dpp v163, v27, v91 row_shl:15 row_mask:0xf bank_mask:0xf
	v_fmac_f32_dpp v164, v20, v116 row_shl:15 row_mask:0xf bank_mask:0xf
	v_fmac_f32_dpp v165, v21, v117 row_shl:15 row_mask:0xf bank_mask:0xf
	v_fmac_f32_dpp v166, v22, v118 row_shl:15 row_mask:0xf bank_mask:0xf
	v_fmac_f32_dpp v167, v23, v119 row_shl:15 row_mask:0xf bank_mask:0xf
	v_fmac_f32_dpp v160, v28, v84 row_shr:2 row_mask:0xf bank_mask:0xf
	v_fmac_f32_dpp v161, v29, v85 row_shr:2 row_mask:0xf bank_mask:0xf
	v_fmac_f32_dpp v162, v30, v86 row_shr:2 row_mask:0xf bank_mask:0xf
	v_fmac_f32_dpp v163, v31, v87 row_shr:2 row_mask:0xf bank_mask:0xf
	v_fmac_f32_dpp v164, v32, v104 row_shr:2 row_mask:0xf bank_mask:0xf
	v_fmac_f32_dpp v165, v33, v105 row_shr:2 row_mask:0xf bank_mask:0xf
	v_fmac_f32_dpp v166, v34, v106 row_shr:2 row_mask:0xf bank_mask:0xf
	v_fmac_f32_dpp v167, v35, v107 row_shr:2 row_mask:0xf bank_mask:0xf
	v_fmac_f32_dpp v160, v24, v84 row_shl:14 row_mask:0xf bank_mask:0xf
	v_fmac_f32_dpp v161, v25, v85 row_shl:14 row_mask:0xf bank_mask:0xf
	v_fmac_f32_dpp v162, v26, v86 row_shl:14 row_mask:0xf bank_mask:0xf
	v_fmac_f32_dpp v163, v27, v87 row_shl:14 row_mask:0xf bank_mask:0xf
	v_fmac_f32_dpp v164, v20, v104 row_shl:14 row_mask:0xf bank_mask:0xf
	v_fmac_f32_dpp v165, v21, v105 row_shl:14 row_mask:0xf bank_mask:0xf
	v_fmac_f32_dpp v166, v22, v106 row_shl:14 row_mask:0xf bank_mask:0xf
	v_fmac_f32_dpp v167, v23, v107 row_shl:14 row_mask:0xf bank_mask:0xf
	v_mul_f32_e32 v168, 0xbfb8aa3b, v160
	v_mul_f32_e32 v169, 0xbfb8aa3b, v161
	v_mul_f32_e32 v170, 0xbfb8aa3b, v162
	v_mul_f32_e32 v171, 0xbfb8aa3b, v163
	v_exp_f32_e32 v168, v168
	v_exp_f32_e32 v169, v169
	v_exp_f32_e32 v170, v170
	v_exp_f32_e32 v171, v171
	v_add_f32_e32 v168, 1.0, v168
	v_add_f32_e32 v169, 1.0, v169
	v_add_f32_e32 v170, 1.0, v170
	v_add_f32_e32 v171, 1.0, v171
	v_rcp_f32_e32 v168, v168
	v_rcp_f32_e32 v169, v169
	v_rcp_f32_e32 v170, v170
	v_rcp_f32_e32 v171, v171
	s_mov_b32 s80, 0x2c000
	s_mov_b32 s81, 0
	v_lshl_add_u64 v[174:175], v[224:225], 0, s[80:81]
	v_mul_f32_e32 v160, v160, v168
	v_mul_f32_e32 v161, v161, v169
	v_mul_f32_e32 v162, v162, v170
	v_mul_f32_e32 v163, v163, v171
	v_mul_f32_e32 v160, v164, v160
	v_mul_f32_e32 v161, v165, v161
	v_mul_f32_e32 v162, v166, v162
	v_mul_f32_e32 v163, v167, v163
	v_cvt_pk_bf16_f32 v172, v160, v161
	v_cvt_pk_bf16_f32 v173, v162, v163
	global_store_dwordx2 v[174:175], v[172:173], off
	v_fma_f32 v208, v100, v8, v124
	v_fma_f32 v209, v101, v9, v125
	v_fma_f32 v210, v102, v10, v126
	v_fma_f32 v211, v103, v11, v127
; DI float silu_fast(float x) { return x * __builtin_amdgcn_rcpf(1.f + __expf(-x)); }
; template <int CTRL> DI float dppf(float v) { return __builtin_bit_cast(float, __builtin_amdgcn_update_dpp(0, __builtin_bit_cast(int, v), CTRL, 0xf, 0xf, true)); }
; DI void Epi::fused(const f32x4 (&acc)[2][2][4][2], int pm, int pn, int wr, int wc, int fr, int fq) const {
;     ...
;                     const float a1 = dppf<0x111>(ca[e]) + dppf<0x10F>(pa[e]), a2 = dppf<0x112>(ca[e]) + dppf<0x10E>(pa[e]);
;                     const float b1 = dppf<0x111>(cb[e]) + dppf<0x10F>(pb[e]), b2 = dppf<0x112>(cb[e]) + dppf<0x10E>(pb[e]);
;                     const float ya = fmaf(wa0[e], a2, fmaf(wa1[e], a1, fmaf(wa2[e], ca[e], ba[e])));
;                     const float yb = fmaf(wb0[e], b2, fmaf(wb1[e], b1, fmaf(wb2[e], cb[e], bb[e])));
;                     o[e] = silu_fast(ya) * yb; }
;                 if (m > 0 || fr >= 2) { u32x2 w; w.x = pk2(o[0], o[1]); w.y = pk2(o[2], o[3]); *(u32x2*)(E.d0 + (size_t)row * FFH + j0) = w; }
;                 if ((m == 0 && fr < 2) || (m == 3 && fr >= 14)) { float* hb = E.f0 + ((size_t)(row >> 6) * 4 + (m == 0 ? fr : fr - 12)) * FF2 + ncol; *(f32x4*)hb = ca; *(f32x4*)(hb + 4) = cb; }
	v_fma_f32 v212, v120, v4, v72
	v_fma_f32 v213, v121, v5, v73
	v_fma_f32 v214, v122, v6, v74
	v_fma_f32 v215, v123, v7, v75
	v_fmac_f32_dpp v208, v8, v88 row_shr:1 row_mask:0xf bank_mask:0xf
	v_fmac_f32_dpp v209, v9, v89 row_shr:1 row_mask:0xf bank_mask:0xf
	v_fmac_f32_dpp v210, v10, v90 row_shr:1 row_mask:0xf bank_mask:0xf
	v_fmac_f32_dpp v211, v11, v91 row_shr:1 row_mask:0xf bank_mask:0xf
	v_fmac_f32_dpp v212, v4, v116 row_shr:1 row_mask:0xf bank_mask:0xf
	v_fmac_f32_dpp v213, v5, v117 row_shr:1 row_mask:0xf bank_mask:0xf
	v_fmac_f32_dpp v214, v6, v118 row_shr:1 row_mask:0xf bank_mask:0xf
	v_fmac_f32_dpp v215, v7, v119 row_shr:1 row_mask:0xf bank_mask:0xf
	v_fmac_f32_dpp v208, v28, v88 row_shl:15 row_mask:0xf bank_mask:0xf
	v_fmac_f32_dpp v209, v29, v89 row_shl:15 row_mask:0xf bank_mask:0xf
	v_fmac_f32_dpp v210, v30, v90 row_shl:15 row_mask:0xf bank_mask:0xf
	v_fmac_f32_dpp v211, v31, v91 row_shl:15 row_mask:0xf bank_mask:0xf
	v_fmac_f32_dpp v212, v32, v116 row_shl:15 row_mask:0xf bank_mask:0xf
	v_fmac_f32_dpp v213, v33, v117 row_shl:15 row_mask:0xf bank_mask:0xf
	v_fmac_f32_dpp v214, v34, v118 row_shl:15 row_mask:0xf bank_mask:0xf
	v_fmac_f32_dpp v215, v35, v119 row_shl:15 row_mask:0xf bank_mask:0xf
	v_fmac_f32_dpp v208, v8, v84 row_shr:2 row_mask:0xf bank_mask:0xf
	v_fmac_f32_dpp v209, v9, v85 row_shr:2 row_mask:0xf bank_mask:0xf
	v_fmac_f32_dpp v210, v10, v86 row_shr:2 row_mask:0xf bank_mask:0xf
	v_fmac_f32_dpp v211, v11, v87 row_shr:2 row_mask:0xf bank_mask:0xf
	v_fmac_f32_dpp v212, v4, v104 row_shr:2 row_mask:0xf bank_mask:0xf
	v_fmac_f32_dpp v213, v5, v105 row_shr:2 row_mask:0xf bank_mask:0xf
	v_fmac_f32_dpp v214, v6, v106 row_shr:2 row_mask:0xf bank_mask:0xf
	v_fmac_f32_dpp v215, v7, v107 row_shr:2 row_mask:0xf bank_mask:0xf
	v_fmac_f32_dpp v208, v28, v84 row_shl:14 row_mask:0xf bank_mask:0xf
	v_fmac_f32_dpp v209, v29, v85 row_shl:14 row_mask:0xf bank_mask:0xf
	v_fmac_f32_dpp v210, v30, v86 row_shl:14 row_mask:0xf bank_mask:0xf
	v_fmac_f32_dpp v211, v31, v87 row_shl:14 row_mask:0xf bank_mask:0xf
	v_fmac_f32_dpp v212, v32, v104 row_shl:14 row_mask:0xf bank_mask:0xf
	v_fmac_f32_dpp v213, v33, v105 row_shl:14 row_mask:0xf bank_mask:0xf
	v_fmac_f32_dpp v214, v34, v106 row_shl:14 row_mask:0xf bank_mask:0xf
	v_fmac_f32_dpp v215, v35, v107 row_shl:14 row_mask:0xf bank_mask:0xf
	v_mul_f32_e32 v216, 0xbfb8aa3b, v208
	v_mul_f32_e32 v217, 0xbfb8aa3b, v209
	v_mul_f32_e32 v218, 0xbfb8aa3b, v210
	v_mul_f32_e32 v219, 0xbfb8aa3b, v211
	v_exp_f32_e32 v216, v216
	v_exp_f32_e32 v217, v217
	v_exp_f32_e32 v218, v218
	v_exp_f32_e32 v219, v219
	v_add_f32_e32 v216, 1.0, v216
	v_add_f32_e32 v217, 1.0, v217
	v_add_f32_e32 v218, 1.0, v218
	v_add_f32_e32 v219, 1.0, v219
	v_rcp_f32_e32 v216, v216
	v_rcp_f32_e32 v217, v217
	v_rcp_f32_e32 v218, v218
	v_rcp_f32_e32 v219, v219
	s_mov_b32 s80, 0x42000
	s_mov_b32 s81, 0
	v_lshl_add_u64 v[222:223], v[224:225], 0, s[80:81]
	v_mul_f32_e32 v208, v208, v216
	v_mul_f32_e32 v209, v209, v217
	v_mul_f32_e32 v210, v210, v218
	v_mul_f32_e32 v211, v211, v219
	v_mul_f32_e32 v208, v212, v208
	v_mul_f32_e32 v209, v213, v209
	v_mul_f32_e32 v210, v214, v210
	v_mul_f32_e32 v211, v215, v211
	v_cvt_pk_bf16_f32 v220, v208, v209
	v_cvt_pk_bf16_f32 v221, v210, v211
	global_store_dwordx2 v[222:223], v[220:221], off
	s_ashr_i32 s80, s71, 6
	s_lshl_b32 s80, s80, 2
	s_add_i32 s80, s80, 8
	v_add_u32_e32 v226, s80, v190
	v_mov_b64_e32 v[222:223], s[8:9]
	s_movk_i32 s80, 0x5800
	v_mad_i64_i32 v[222:223], s[78:79], v226, s80, v[222:223]
	v_lshl_add_u64 v[222:223], v[228:229], 2, v[222:223]
	s_and_saveexec_b64 s[76:77], s[42:43]
	global_store_dwordx4 v[222:223], v[8:11], off
	global_store_dwordx4 v[222:223], v[4:7], off offset:16
	s_or_b64 exec, exec, s[76:77]
